# accumulator zeroing before each GEMM K-loop: 128 v_mov_b32 replaced by 64 v_mov_b64 (padded, no address changes)
# baseline (speedup 1.0000x reference)
; #define PG8_STAGE(bufoff, gbase, voff) do { _Pragma("unroll") for (int _i = 0; _i < 2; ++_i) \
;         __builtin_amdgcn_global_load_lds((const unsigned*)((const char*)(gbase) + (voff)[_i]), (PG8_LAS unsigned*)(lds + (bufoff) + ldsw + _i * 8192), 16, 0, 0); } while (0)
; #define PG8_LDA(dst, b, h) do { _Pragma("unroll") for (int m = 0; m < 4; ++m) _Pragma("unroll") for (int k = 0; k < 2; ++k) dst[m][k] = *(const PG8_LAS bf16x8*)(lds + PG8_SA(b, h) + aoff + m * 2048 + k * 1024); } while (0)
; #define PG8_LDB(dst, b, h) do { _Pragma("unroll") for (int n = 0; n < 2; ++n) _Pragma("unroll") for (int k = 0; k < 2; ++k) dst[n][k] = *(const PG8_LAS bf16x8*)(lds + PG8_SB(b, h) + boff + n * 2048 + k * 1024); } while (0)
; #define PG8_WAIT_V(n) asm volatile("s_waitcnt vmcnt(" #n ")" ::: "memory")
; #define PG8_WAIT_L(n) asm volatile("s_waitcnt lgkmcnt(" #n ")" ::: "memory")
; #define PG8_BAR __builtin_amdgcn_s_barrier()
; #define PG8_SCHED __builtin_amdgcn_sched_barrier(0)
; template <class Epi, class Sched, bool ALIGN_EPI = false, bool SP2 = false>
; __device__ __forceinline__ void gemm_phase(PG8_LAS unsigned char* lds, const Gemm g, const Sched& S, const Epi& E) {
;     ...
;         const bool has_next = S.next(ui + 1, nxt);
;         const char* nA = has_next ? (const char*)g.A + (size_t)nxt.pm * tstep : cA; const char* nB = has_next ? (const char*)g.Bt + (size_t)nxt.pn * tstep : cB;
;         for (int t = 0; t < nt; t += 2) {
;             const bool last = (t == nt - 2);
;             const char* a1 = cA + (size_t)(t + 1) * kstep;
;             const char* a2 = last ? nA : cA + (size_t)(t + 2) * kstep; const char* b2 = last ? nB : cB + (size_t)(t + 2) * kstep;
;             const char* a3 = a2 + kstep; const char* b3 = b2 + kstep;
;             if (last && has_next) S.a_ready(nxt);
;             if constexpr (SP2) {
;             PG8_LDB(B0, 0, 0); PG8_LDB(B1, 0, 1); PG8_SCHED; PG8_LDA(At, 0, 0); PG8_STAGE(PG8_SA(1, 1), a1 + hstep, voffA);
;             PG8_WAIT_V(8); PG8_WAIT_L(0); PG8_BAR; PG8_MMA(0, 0, At, B0); PG8_MMA(0, 1, At, B1); PG8_BAR; PG8_SCHED;
;     ...
; #pragma unroll
;         for (int a = 0; a < 2; ++a)
; #pragma unroll
;             for (int b = 0; b < 2; ++b)
; #pragma unroll
;                 for (int m = 0; m < 4; ++m)
; #pragma unroll
;                     for (int n = 0; n < 2; ++n) acc[a][b][m][n] = (f32x4){0.f, 0.f, 0.f, 0.f};
.LBB0_66:
	s_ashr_i32 s1, s0, 31
	s_lshl_b64 s[38:39], s[0:1], 19
	s_add_u32 s38, s26, s38
	s_addc_u32 s39, s27, s39
	s_and_b64 s[56:57], s[12:13], exec
	s_cselect_b32 s1, s39, s37
	s_cselect_b32 s79, s38, s36
	s_ashr_i32 s21, s20, 31
	s_lshl_b64 s[56:57], s[20:21], 19
	s_add_u32 s96, s75, s56
	s_addc_u32 s97, s82, s57
	s_and_b64 s[56:57], s[12:13], exec
	s_cselect_b32 s21, s97, s15
	s_cselect_b32 s45, s96, s14
	s_add_u32 s52, s14, 0x100
	s_addc_u32 s54, s15, 0
	s_add_u32 s14, s36, 0x40080
	s_addc_u32 s15, s37, 0
	s_mov_b32 s56, -2
	v_mov_b64_e32 v[2:3], 0
	v_mov_b64_e32 v[4:5], 0
	v_mov_b64_e32 v[6:7], 0
	v_mov_b64_e32 v[8:9], 0
	v_mov_b64_e32 v[10:11], 0
	v_mov_b64_e32 v[12:13], 0
	v_mov_b64_e32 v[14:15], 0
	v_mov_b64_e32 v[16:17], 0
	v_mov_b64_e32 v[18:19], 0
	v_mov_b64_e32 v[20:21], 0
	v_mov_b64_e32 v[22:23], 0
	v_mov_b64_e32 v[24:25], 0
	v_mov_b64_e32 v[26:27], 0
	v_mov_b64_e32 v[28:29], 0
	v_mov_b64_e32 v[30:31], 0
	v_mov_b64_e32 v[32:33], 0
	v_mov_b64_e32 v[34:35], 0
	v_mov_b64_e32 v[36:37], 0
	v_mov_b64_e32 v[38:39], 0
	v_mov_b64_e32 v[40:41], 0
	v_mov_b64_e32 v[42:43], 0
	v_mov_b64_e32 v[44:45], 0
	v_mov_b64_e32 v[46:47], 0
	v_mov_b64_e32 v[48:49], 0
	v_mov_b64_e32 v[50:51], 0
	v_mov_b64_e32 v[52:53], 0
	v_mov_b64_e32 v[54:55], 0
	v_mov_b64_e32 v[56:57], 0
	v_mov_b64_e32 v[58:59], 0
	v_mov_b64_e32 v[60:61], 0
	v_mov_b64_e32 v[62:63], 0
	v_mov_b64_e32 v[64:65], 0
	v_mov_b64_e32 v[66:67], 0
	v_mov_b64_e32 v[68:69], 0
	v_mov_b64_e32 v[70:71], 0
	v_mov_b64_e32 v[72:73], 0
	v_mov_b64_e32 v[74:75], 0
	v_mov_b64_e32 v[76:77], 0
	v_mov_b64_e32 v[78:79], 0
	v_mov_b64_e32 v[80:81], 0
	v_mov_b64_e32 v[82:83], 0
	v_mov_b64_e32 v[84:85], 0
	v_mov_b64_e32 v[86:87], 0
	v_mov_b64_e32 v[88:89], 0
	v_mov_b64_e32 v[90:91], 0
	v_mov_b64_e32 v[92:93], 0
	v_mov_b64_e32 v[94:95], 0
	v_mov_b64_e32 v[96:97], 0
	v_mov_b64_e32 v[122:123], 0
	v_mov_b64_e32 v[124:125], 0
	v_mov_b64_e32 v[126:127], 0
	v_mov_b64_e32 v[128:129], 0
	v_mov_b64_e32 v[130:131], 0
	v_mov_b64_e32 v[132:133], 0
	v_mov_b64_e32 v[134:135], 0
	v_mov_b64_e32 v[136:137], 0
	v_mov_b64_e32 v[138:139], 0
	v_mov_b64_e32 v[140:141], 0
	v_mov_b64_e32 v[142:143], 0
	v_mov_b64_e32 v[144:145], 0
	v_mov_b64_e32 v[146:147], 0
	v_mov_b64_e32 v[148:149], 0
	v_mov_b64_e32 v[150:151], 0
	v_mov_b64_e32 v[152:153], 0
	s_branch .Lz64_0
	s_nop 0
	s_nop 0
	s_nop 0
	s_nop 0
	s_nop 0
	s_nop 0
	s_nop 0
	s_nop 0
	s_nop 0
	s_nop 0
	s_nop 0
	s_nop 0
	s_nop 0
	s_nop 0
	s_nop 0
	s_nop 0
	s_nop 0
	s_nop 0
	s_nop 0
	s_nop 0
	s_nop 0
	s_nop 0
	s_nop 0
	s_nop 0
	s_nop 0
	s_nop 0
	s_nop 0
	s_nop 0
	s_nop 0
	s_nop 0
	s_nop 0
	s_nop 0
	s_nop 0
	s_nop 0
	s_nop 0
	s_nop 0
	s_nop 0
	s_nop 0
	s_nop 0
	s_nop 0
	s_nop 0
	s_nop 0
	s_nop 0
	s_nop 0
	s_nop 0
	s_nop 0
	s_nop 0
	s_nop 0
	s_nop 0
	s_nop 0
	s_nop 0
	s_nop 0
	s_nop 0
	s_nop 0
	s_nop 0
	s_nop 0
	s_nop 0
	s_nop 0
	s_nop 0
	s_nop 0
	s_nop 0
	s_nop 0
	s_nop 0
.Lz64_0:
.LBB0_67:
	s_add_u32 s36, s14, 0xfffc0080
	s_addc_u32 s37, s15, -1
	s_add_i32 s57, 0, 0x10000
	s_cmp_eq_u32 s56, 12
	s_cselect_b32 vcc_hi, s1, s37
	s_cselect_b32 vcc_lo, s79, s36
	s_cselect_b32 s37, s21, s54
	s_cselect_b32 s36, s45, s52
	s_add_i32 s60, 0, 0x14000
	v_add_u32_e32 v110, s57, v195
	v_add_u32_e32 v158, s60, v195
	ds_read_b128 v[98:101], v110
	ds_read_b128 v[102:105], v110 offset:1024
	ds_read_b128 v[106:109], v110 offset:2048
	ds_read_b128 v[110:113], v110 offset:3072
	ds_read_b128 v[114:117], v158
	ds_read_b128 v[118:121], v158 offset:1024
	ds_read_b128 v[154:157], v158 offset:2048
	ds_read_b128 v[158:161], v158 offset:3072
	v_lshl_add_u64 v[240:241], s[14:15], 0, v[188:189]
	s_add_i32 m0, s84, 0xc000
	ds_read_b128 v[162:165], v207
	ds_read_b128 v[166:169], v207 offset:1024
	ds_read_b128 v[190:193], v207 offset:2048
	ds_read_b128 v[208:211], v207 offset:3072
	ds_read_b128 v[224:227], v207 offset:4096
	ds_read_b128 v[228:231], v207 offset:5120
	ds_read_b128 v[232:235], v207 offset:6144
	ds_read_b128 v[236:239], v207 offset:7168
	global_load_lds_dwordx4 v[240:241], off
	v_lshl_add_u64 v[240:241], s[14:15], 0, v[186:187]
	s_add_i32 m0, s84, 0xe000
	s_nop 0
	global_load_lds_dwordx4 v[240:241], off
	s_waitcnt vmcnt(8)
	s_waitcnt lgkmcnt(0)
	s_barrier
	s_setprio 1
	s_waitcnt lgkmcnt(0)
	v_mfma_f32_16x16x32_bf16 v[150:153], v[98:101], v[162:165], v[150:153]
	v_mfma_f32_16x16x32_bf16 v[70:73], v[106:109], v[162:165], v[70:73]
	v_mfma_f32_16x16x32_bf16 v[142:145], v[98:101], v[190:193], v[142:145]
	v_mfma_f32_16x16x32_bf16 v[62:65], v[106:109], v[190:193], v[62:65]
	v_mfma_f32_16x16x32_bf16 v[134:137], v[98:101], v[224:227], v[134:137]
	v_mfma_f32_16x16x32_bf16 v[54:57], v[106:109], v[224:227], v[54:57]
	v_mfma_f32_16x16x32_bf16 v[126:129], v[98:101], v[232:235], v[126:129]
	v_mfma_f32_16x16x32_bf16 v[46:49], v[106:109], v[232:235], v[46:49]
	v_mfma_f32_16x16x32_bf16 v[150:153], v[102:105], v[166:169], v[150:153]
	v_mfma_f32_16x16x32_bf16 v[70:73], v[110:113], v[166:169], v[70:73]
	v_mfma_f32_16x16x32_bf16 v[142:145], v[102:105], v[208:211], v[142:145]
	v_mfma_f32_16x16x32_bf16 v[62:65], v[110:113], v[208:211], v[62:65]
	v_mfma_f32_16x16x32_bf16 v[134:137], v[102:105], v[228:231], v[134:137]
	v_mfma_f32_16x16x32_bf16 v[54:57], v[110:113], v[228:231], v[54:57]
	v_mfma_f32_16x16x32_bf16 v[126:129], v[102:105], v[236:239], v[126:129]
	v_mfma_f32_16x16x32_bf16 v[46:49], v[110:113], v[236:239], v[46:49]
	s_setprio 0
	s_setprio 1
	v_mfma_f32_16x16x32_bf16 v[146:149], v[114:117], v[162:165], v[146:149]
	v_mfma_f32_16x16x32_bf16 v[66:69], v[154:157], v[162:165], v[66:69]
	v_mfma_f32_16x16x32_bf16 v[138:141], v[114:117], v[190:193], v[138:141]
	v_mfma_f32_16x16x32_bf16 v[58:61], v[154:157], v[190:193], v[58:61]
	v_mfma_f32_16x16x32_bf16 v[130:133], v[114:117], v[224:227], v[130:133]
	v_mfma_f32_16x16x32_bf16 v[50:53], v[154:157], v[224:227], v[50:53]
	v_mfma_f32_16x16x32_bf16 v[122:125], v[114:117], v[232:235], v[122:125]
	v_mfma_f32_16x16x32_bf16 v[42:45], v[154:157], v[232:235], v[42:45]
	v_mfma_f32_16x16x32_bf16 v[146:149], v[118:121], v[166:169], v[146:149]
	v_mfma_f32_16x16x32_bf16 v[66:69], v[158:161], v[166:169], v[66:69]
	v_mfma_f32_16x16x32_bf16 v[138:141], v[118:121], v[208:211], v[138:141]
	v_mfma_f32_16x16x32_bf16 v[58:61], v[158:161], v[208:211], v[58:61]
	v_mfma_f32_16x16x32_bf16 v[130:133], v[118:121], v[228:231], v[130:133]
	v_mfma_f32_16x16x32_bf16 v[50:53], v[158:161], v[228:231], v[50:53]
	v_mfma_f32_16x16x32_bf16 v[122:125], v[118:121], v[236:239], v[122:125]
	v_mfma_f32_16x16x32_bf16 v[42:45], v[158:161], v[236:239], v[42:45]
	s_setprio 0
	s_barrier
; #define PG8_STAGE(bufoff, gbase, voff) do { _Pragma("unroll") for (int _i = 0; _i < 2; ++_i) \
;         __builtin_amdgcn_global_load_lds((const unsigned*)((const char*)(gbase) + (voff)[_i]), (PG8_LAS unsigned*)(lds + (bufoff) + ldsw + _i * 8192), 16, 0, 0); } while (0)
; #define PG8_LDA(dst, b, h) do { _Pragma("unroll") for (int m = 0; m < 4; ++m) _Pragma("unroll") for (int k = 0; k < 2; ++k) dst[m][k] = *(const PG8_LAS bf16x8*)(lds + PG8_SA(b, h) + aoff + m * 2048 + k * 1024); } while (0)
; #define PG8_LDB(dst, b, h) do { _Pragma("unroll") for (int n = 0; n < 2; ++n) _Pragma("unroll") for (int k = 0; k < 2; ++k) dst[n][k] = *(const PG8_LAS bf16x8*)(lds + PG8_SB(b, h) + boff + n * 2048 + k * 1024); } while (0)
; #define PG8_MMA(ai, bj, At, Bt) do { __builtin_amdgcn_s_setprio(1); _Pragma("unroll") for (int m = 0; m < 4; ++m) _Pragma("unroll") for (int n = 0; n < 2; ++n) _Pragma("unroll") for (int k = 0; k < 2; ++k) \
;         acc[ai][bj][m][n] = __builtin_amdgcn_mfma_f32_16x16x32_bf16(Bt[n][k], At[m][k], acc[ai][bj][m][n], 0, 0, 0); __builtin_amdgcn_s_setprio(0); } while (0)
; #define PG8_WAIT_V(n) asm volatile("s_waitcnt vmcnt(" #n ")" ::: "memory")
; #define PG8_WAIT_L(n) asm volatile("s_waitcnt lgkmcnt(" #n ")" ::: "memory")
; #define PG8_BAR __builtin_amdgcn_s_barrier()
; #define PG8_SCHED __builtin_amdgcn_sched_barrier(0)
; template <class Epi, class Sched, bool ALIGN_EPI = false, bool SP2 = false>
; __device__ __forceinline__ void gemm_phase(PG8_LAS unsigned char* lds, const Gemm g, const Sched& S, const Epi& E) {
;     ...
;             PG8_LDA(At, 0, 1); PG8_STAGE(PG8_SB(0, 0), b2, voffB); PG8_STAGE(PG8_SB(0, 1), b2 + hstep, voffB); PG8_STAGE(PG8_SA(0, 0), a2, voffA);
;             PG8_WAIT_V(8); PG8_WAIT_L(0); PG8_BAR; PG8_MMA(1, 0, At, B0); PG8_MMA(1, 1, At, B1); PG8_BAR; PG8_SCHED;
;             PG8_LDB(B0, 1, 0); PG8_LDB(B1, 1, 1); PG8_SCHED; PG8_LDA(At, 1, 0); PG8_STAGE(PG8_SA(0, 1), a2 + hstep, voffA);
;             PG8_WAIT_V(8); PG8_WAIT_L(0); PG8_BAR; PG8_MMA(0, 0, At, B0); PG8_MMA(0, 1, At, B1); PG8_BAR; PG8_SCHED;
	s_add_i32 s57, s57, s83
	v_lshl_add_u64 v[240:241], s[36:37], 0, v[0:1]
	s_mov_b32 m0, s57
	ds_read_b128 v[162:165], v207 offset:16384
	ds_read_b128 v[166:169], v207 offset:17408
	ds_read_b128 v[190:193], v207 offset:18432
	ds_read_b128 v[208:211], v207 offset:19456
	ds_read_b128 v[224:227], v207 offset:20480
	ds_read_b128 v[228:231], v207 offset:21504
	ds_read_b128 v[232:235], v207 offset:22528
	ds_read_b128 v[236:239], v207 offset:23552
	global_load_lds_dwordx4 v[240:241], off
	s_add_i32 m0, s57, 0x2000
	s_add_u32 s58, s36, 0x40000
	v_lshl_add_u64 v[242:243], s[36:37], 0, v[182:183]
	s_addc_u32 s59, s37, 0
	s_add_i32 s57, s60, s83
	global_load_lds_dwordx4 v[242:243], off
	v_lshl_add_u64 v[244:245], s[58:59], 0, v[0:1]
	s_mov_b32 m0, s57
	v_lshl_add_u64 v[246:247], vcc, 0, v[180:181]
	global_load_lds_dwordx4 v[244:245], off
	v_lshl_add_u64 v[244:245], s[58:59], 0, v[182:183]
	s_add_i32 m0, s57, 0x2000
	s_nop 0
	global_load_lds_dwordx4 v[244:245], off
	v_lshl_add_u64 v[244:245], vcc, 0, v[178:179]
	s_mov_b32 m0, s84
	s_nop 0
	global_load_lds_dwordx4 v[244:245], off
	s_mov_b32 m0, s93
	s_nop 0
	global_load_lds_dwordx4 v[246:247], off
	s_waitcnt vmcnt(8)
	s_waitcnt lgkmcnt(0)
	s_barrier
	s_setprio 1
	s_waitcnt lgkmcnt(0)
	v_mfma_f32_16x16x32_bf16 v[94:97], v[98:101], v[162:165], v[94:97]
	v_mfma_f32_16x16x32_bf16 v[38:41], v[106:109], v[162:165], v[38:41]
	v_mfma_f32_16x16x32_bf16 v[86:89], v[98:101], v[190:193], v[86:89]
	v_mfma_f32_16x16x32_bf16 v[30:33], v[106:109], v[190:193], v[30:33]
	v_mfma_f32_16x16x32_bf16 v[78:81], v[98:101], v[224:227], v[78:81]
	v_mfma_f32_16x16x32_bf16 v[22:25], v[106:109], v[224:227], v[22:25]
	v_mfma_f32_16x16x32_bf16 v[14:17], v[98:101], v[232:235], v[14:17]
	v_mfma_f32_16x16x32_bf16 v[10:13], v[106:109], v[232:235], v[10:13]
	v_mfma_f32_16x16x32_bf16 v[94:97], v[102:105], v[166:169], v[94:97]
	v_mfma_f32_16x16x32_bf16 v[38:41], v[110:113], v[166:169], v[38:41]
	v_mfma_f32_16x16x32_bf16 v[86:89], v[102:105], v[208:211], v[86:89]
	v_mfma_f32_16x16x32_bf16 v[30:33], v[110:113], v[208:211], v[30:33]
	v_mfma_f32_16x16x32_bf16 v[78:81], v[102:105], v[228:231], v[78:81]
	v_mfma_f32_16x16x32_bf16 v[22:25], v[110:113], v[228:231], v[22:25]
	v_mfma_f32_16x16x32_bf16 v[14:17], v[102:105], v[236:239], v[14:17]
	v_mfma_f32_16x16x32_bf16 v[10:13], v[110:113], v[236:239], v[10:13]
	s_setprio 0
	s_setprio 1
	v_mfma_f32_16x16x32_bf16 v[90:93], v[114:117], v[162:165], v[90:93]
	v_mfma_f32_16x16x32_bf16 v[34:37], v[154:157], v[162:165], v[34:37]
	v_mfma_f32_16x16x32_bf16 v[82:85], v[114:117], v[190:193], v[82:85]
	v_mfma_f32_16x16x32_bf16 v[26:29], v[154:157], v[190:193], v[26:29]
	v_mfma_f32_16x16x32_bf16 v[74:77], v[114:117], v[224:227], v[74:77]
	v_mfma_f32_16x16x32_bf16 v[18:21], v[154:157], v[224:227], v[18:21]
	v_mfma_f32_16x16x32_bf16 v[6:9], v[114:117], v[232:235], v[6:9]
	v_mfma_f32_16x16x32_bf16 v[2:5], v[154:157], v[232:235], v[2:5]
	v_mfma_f32_16x16x32_bf16 v[90:93], v[118:121], v[166:169], v[90:93]
	v_mfma_f32_16x16x32_bf16 v[34:37], v[158:161], v[166:169], v[34:37]
	v_mfma_f32_16x16x32_bf16 v[82:85], v[118:121], v[208:211], v[82:85]
	v_mfma_f32_16x16x32_bf16 v[26:29], v[158:161], v[208:211], v[26:29]
	v_mfma_f32_16x16x32_bf16 v[74:77], v[118:121], v[228:231], v[74:77]
	v_mfma_f32_16x16x32_bf16 v[18:21], v[158:161], v[228:231], v[18:21]
	v_mfma_f32_16x16x32_bf16 v[6:9], v[118:121], v[236:239], v[6:9]
	v_mfma_f32_16x16x32_bf16 v[2:5], v[158:161], v[236:239], v[2:5]
	s_setprio 0
	s_barrier
	s_add_i32 s57, 0, 0x18000
	s_add_i32 s60, 0, 0x1c000
	v_add_u32_e32 v110, s57, v195
	v_add_u32_e32 v158, s60, v195
	ds_read_b128 v[98:101], v110
	ds_read_b128 v[102:105], v110 offset:1024
	ds_read_b128 v[106:109], v110 offset:2048
	ds_read_b128 v[110:113], v110 offset:3072
	ds_read_b128 v[114:117], v158
	ds_read_b128 v[118:121], v158 offset:1024
	ds_read_b128 v[154:157], v158 offset:2048
	ds_read_b128 v[158:161], v158 offset:3072
	s_add_u32 s58, vcc_lo, 0x40000
	s_addc_u32 s59, vcc_hi, 0
	s_mov_b32 m0, s72
	v_lshl_add_u64 v[248:249], s[58:59], 0, v[178:179]
	ds_read_b128 v[162:165], v207 offset:32768
	ds_read_b128 v[166:169], v207 offset:33792
	ds_read_b128 v[190:193], v207 offset:34816
	ds_read_b128 v[208:211], v207 offset:35840
	ds_read_b128 v[224:227], v207 offset:36864
	ds_read_b128 v[228:231], v207 offset:37888
	ds_read_b128 v[232:235], v207 offset:38912
	ds_read_b128 v[236:239], v207 offset:39936
	global_load_lds_dwordx4 v[248:249], off
	v_lshl_add_u64 v[248:249], s[58:59], 0, v[180:181]
	s_mov_b32 m0, s55
	s_nop 0
	global_load_lds_dwordx4 v[248:249], off
	s_waitcnt vmcnt(8)
	s_waitcnt lgkmcnt(0)
	s_barrier
; #define PG8_STAGE(bufoff, gbase, voff) do { _Pragma("unroll") for (int _i = 0; _i < 2; ++_i) \
;         __builtin_amdgcn_global_load_lds((const unsigned*)((const char*)(gbase) + (voff)[_i]), (PG8_LAS unsigned*)(lds + (bufoff) + ldsw + _i * 8192), 16, 0, 0); } while (0)
; #define PG8_LDA(dst, b, h) do { _Pragma("unroll") for (int m = 0; m < 4; ++m) _Pragma("unroll") for (int k = 0; k < 2; ++k) dst[m][k] = *(const PG8_LAS bf16x8*)(lds + PG8_SA(b, h) + aoff + m * 2048 + k * 1024); } while (0)
; #define PG8_MMA(ai, bj, At, Bt) do { __builtin_amdgcn_s_setprio(1); _Pragma("unroll") for (int m = 0; m < 4; ++m) _Pragma("unroll") for (int n = 0; n < 2; ++n) _Pragma("unroll") for (int k = 0; k < 2; ++k) \
;         acc[ai][bj][m][n] = __builtin_amdgcn_mfma_f32_16x16x32_bf16(Bt[n][k], At[m][k], acc[ai][bj][m][n], 0, 0, 0); __builtin_amdgcn_s_setprio(0); } while (0)
; #define PG8_WAIT_V(n) asm volatile("s_waitcnt vmcnt(" #n ")" ::: "memory")
; #define PG8_WAIT_L(n) asm volatile("s_waitcnt lgkmcnt(" #n ")" ::: "memory")
; #define PG8_BAR __builtin_amdgcn_s_barrier()
; #define PG8_SCHED __builtin_amdgcn_sched_barrier(0)
; template <class Epi, class Sched, bool ALIGN_EPI = false, bool SP2 = false>
; __device__ __forceinline__ void gemm_phase(PG8_LAS unsigned char* lds, const Gemm g, const Sched& S, const Epi& E) {
;     ...
;             PG8_WAIT_V(8); PG8_WAIT_L(0); PG8_BAR; PG8_MMA(0, 0, At, B0); PG8_MMA(0, 1, At, B1); PG8_BAR; PG8_SCHED;
;             PG8_LDA(At, 1, 1); PG8_STAGE(PG8_SB(1, 0), b3, voffB); PG8_STAGE(PG8_SB(1, 1), b3 + hstep, voffB); PG8_STAGE(PG8_SA(1, 0), a3, voffA);
;             PG8_WAIT_V(8); PG8_WAIT_L(0); PG8_BAR; PG8_MMA(1, 0, At, B0); PG8_MMA(1, 1, At, B1); PG8_BAR; PG8_SCHED;
;     ...
;         if constexpr (ALIGN_EPI) { if (wr == 0) PG8_BAR; }
;         if constexpr (!Epi::AFTER_DRAIN) { E(acc, cur, wr, wc, fr, fq); S.done(cur); }
;         if (!has_next) break;
	s_setprio 1
	s_waitcnt lgkmcnt(0)
	v_mfma_f32_16x16x32_bf16 v[150:153], v[98:101], v[162:165], v[150:153]
	v_mfma_f32_16x16x32_bf16 v[70:73], v[106:109], v[162:165], v[70:73]
	v_mfma_f32_16x16x32_bf16 v[142:145], v[98:101], v[190:193], v[142:145]
	v_mfma_f32_16x16x32_bf16 v[62:65], v[106:109], v[190:193], v[62:65]
	v_mfma_f32_16x16x32_bf16 v[134:137], v[98:101], v[224:227], v[134:137]
	v_mfma_f32_16x16x32_bf16 v[54:57], v[106:109], v[224:227], v[54:57]
	v_mfma_f32_16x16x32_bf16 v[126:129], v[98:101], v[232:235], v[126:129]
	v_mfma_f32_16x16x32_bf16 v[46:49], v[106:109], v[232:235], v[46:49]
	v_mfma_f32_16x16x32_bf16 v[150:153], v[102:105], v[166:169], v[150:153]
	v_mfma_f32_16x16x32_bf16 v[70:73], v[110:113], v[166:169], v[70:73]
	v_mfma_f32_16x16x32_bf16 v[142:145], v[102:105], v[208:211], v[142:145]
	v_mfma_f32_16x16x32_bf16 v[62:65], v[110:113], v[208:211], v[62:65]
	v_mfma_f32_16x16x32_bf16 v[134:137], v[102:105], v[228:231], v[134:137]
	v_mfma_f32_16x16x32_bf16 v[54:57], v[110:113], v[228:231], v[54:57]
	v_mfma_f32_16x16x32_bf16 v[126:129], v[102:105], v[236:239], v[126:129]
	v_mfma_f32_16x16x32_bf16 v[46:49], v[110:113], v[236:239], v[46:49]
	s_setprio 0
	s_setprio 1
	v_mfma_f32_16x16x32_bf16 v[146:149], v[114:117], v[162:165], v[146:149]
	v_mfma_f32_16x16x32_bf16 v[66:69], v[154:157], v[162:165], v[66:69]
	v_mfma_f32_16x16x32_bf16 v[138:141], v[114:117], v[190:193], v[138:141]
	v_mfma_f32_16x16x32_bf16 v[58:61], v[154:157], v[190:193], v[58:61]
	v_mfma_f32_16x16x32_bf16 v[130:133], v[114:117], v[224:227], v[130:133]
	v_mfma_f32_16x16x32_bf16 v[50:53], v[154:157], v[224:227], v[50:53]
	v_mfma_f32_16x16x32_bf16 v[122:125], v[114:117], v[232:235], v[122:125]
	v_mfma_f32_16x16x32_bf16 v[42:45], v[154:157], v[232:235], v[42:45]
	v_mfma_f32_16x16x32_bf16 v[146:149], v[118:121], v[166:169], v[146:149]
	v_mfma_f32_16x16x32_bf16 v[66:69], v[158:161], v[166:169], v[66:69]
	v_mfma_f32_16x16x32_bf16 v[138:141], v[118:121], v[208:211], v[138:141]
	v_mfma_f32_16x16x32_bf16 v[58:61], v[158:161], v[208:211], v[58:61]
	v_mfma_f32_16x16x32_bf16 v[130:133], v[118:121], v[228:231], v[130:133]
	v_mfma_f32_16x16x32_bf16 v[50:53], v[158:161], v[228:231], v[50:53]
	v_mfma_f32_16x16x32_bf16 v[122:125], v[118:121], v[236:239], v[122:125]
	v_mfma_f32_16x16x32_bf16 v[42:45], v[158:161], v[236:239], v[42:45]
	s_setprio 0
	s_barrier
	s_add_i32 s57, s57, s83
	v_lshl_add_u64 v[240:241], v[240:241], 0, s[88:89]
	s_mov_b32 m0, s57
	ds_read_b128 v[162:165], v207 offset:49152
	ds_read_b128 v[166:169], v207 offset:50176
	ds_read_b128 v[190:193], v207 offset:51200
	ds_read_b128 v[208:211], v207 offset:52224
	ds_read_b128 v[224:227], v207 offset:53248
	ds_read_b128 v[228:231], v207 offset:54272
	ds_read_b128 v[232:235], v207 offset:55296
	ds_read_b128 v[236:239], v207 offset:56320
	global_load_lds_dwordx4 v[240:241], off
	s_add_i32 m0, s57, 0x2000
	s_add_u32 s36, s36, 0x40080
	v_lshl_add_u64 v[240:241], v[242:243], 0, s[88:89]
	s_addc_u32 s37, s37, 0
	s_add_i32 s57, s60, s83
	global_load_lds_dwordx4 v[240:241], off
	v_lshl_add_u64 v[240:241], s[36:37], 0, v[0:1]
	s_mov_b32 m0, s57
	s_nop 0
	global_load_lds_dwordx4 v[240:241], off
	v_lshl_add_u64 v[240:241], s[36:37], 0, v[182:183]
	s_add_i32 m0, s57, 0x2000
	s_nop 0
	global_load_lds_dwordx4 v[240:241], off
	v_lshl_add_u64 v[240:241], v[244:245], 0, s[88:89]
	s_mov_b32 m0, s47
	s_nop 0
	global_load_lds_dwordx4 v[240:241], off
	v_lshl_add_u64 v[240:241], v[246:247], 0, s[88:89]
	s_mov_b32 m0, s51
	s_nop 0
	global_load_lds_dwordx4 v[240:241], off
	s_waitcnt vmcnt(8)
	s_waitcnt lgkmcnt(0)
	s_barrier
	s_setprio 1
	s_waitcnt lgkmcnt(0)
	v_mfma_f32_16x16x32_bf16 v[94:97], v[98:101], v[162:165], v[94:97]
	v_mfma_f32_16x16x32_bf16 v[38:41], v[106:109], v[162:165], v[38:41]
	v_mfma_f32_16x16x32_bf16 v[86:89], v[98:101], v[190:193], v[86:89]
	v_mfma_f32_16x16x32_bf16 v[30:33], v[106:109], v[190:193], v[30:33]
	v_mfma_f32_16x16x32_bf16 v[78:81], v[98:101], v[224:227], v[78:81]
	v_mfma_f32_16x16x32_bf16 v[22:25], v[106:109], v[224:227], v[22:25]
	v_mfma_f32_16x16x32_bf16 v[14:17], v[98:101], v[232:235], v[14:17]
	v_mfma_f32_16x16x32_bf16 v[10:13], v[106:109], v[232:235], v[10:13]
	v_mfma_f32_16x16x32_bf16 v[94:97], v[102:105], v[166:169], v[94:97]
	v_mfma_f32_16x16x32_bf16 v[38:41], v[110:113], v[166:169], v[38:41]
	v_mfma_f32_16x16x32_bf16 v[86:89], v[102:105], v[208:211], v[86:89]
	v_mfma_f32_16x16x32_bf16 v[30:33], v[110:113], v[208:211], v[30:33]
	v_mfma_f32_16x16x32_bf16 v[78:81], v[102:105], v[228:231], v[78:81]
	v_mfma_f32_16x16x32_bf16 v[22:25], v[110:113], v[228:231], v[22:25]
	v_mfma_f32_16x16x32_bf16 v[14:17], v[102:105], v[236:239], v[14:17]
	v_mfma_f32_16x16x32_bf16 v[10:13], v[110:113], v[236:239], v[10:13]
	s_setprio 0
	s_setprio 1
	v_mfma_f32_16x16x32_bf16 v[90:93], v[114:117], v[162:165], v[90:93]
	v_mfma_f32_16x16x32_bf16 v[34:37], v[154:157], v[162:165], v[34:37]
	v_mfma_f32_16x16x32_bf16 v[82:85], v[114:117], v[190:193], v[82:85]
	v_mfma_f32_16x16x32_bf16 v[26:29], v[154:157], v[190:193], v[26:29]
	v_mfma_f32_16x16x32_bf16 v[74:77], v[114:117], v[224:227], v[74:77]
	v_mfma_f32_16x16x32_bf16 v[18:21], v[154:157], v[224:227], v[18:21]
	v_mfma_f32_16x16x32_bf16 v[6:9], v[114:117], v[232:235], v[6:9]
	v_mfma_f32_16x16x32_bf16 v[2:5], v[154:157], v[232:235], v[2:5]
	v_mfma_f32_16x16x32_bf16 v[90:93], v[118:121], v[166:169], v[90:93]
	v_mfma_f32_16x16x32_bf16 v[34:37], v[158:161], v[166:169], v[34:37]
	v_mfma_f32_16x16x32_bf16 v[82:85], v[118:121], v[208:211], v[82:85]
	v_mfma_f32_16x16x32_bf16 v[26:29], v[158:161], v[208:211], v[26:29]
	v_mfma_f32_16x16x32_bf16 v[74:77], v[118:121], v[228:231], v[74:77]
	v_mfma_f32_16x16x32_bf16 v[18:21], v[158:161], v[228:231], v[18:21]
	v_mfma_f32_16x16x32_bf16 v[6:9], v[118:121], v[236:239], v[6:9]
	v_mfma_f32_16x16x32_bf16 v[2:5], v[158:161], v[236:239], v[2:5]
	s_setprio 0
	s_barrier
	s_add_i32 s56, s56, 2
	s_add_u32 s52, s52, 0x100
	s_addc_u32 s54, s54, 0
	s_add_u32 s14, s14, 0x100
	s_addc_u32 s15, s15, 0
	s_cmp_gt_u32 s56, 13
	s_cbranch_scc0 .LBB0_67
	s_and_b64 vcc, exec, s[34:35]
	s_cbranch_vccz .LBB0_70
	s_barrier

; #define PG8_STAGE(bufoff, gbase, voff) do { _Pragma("unroll") for (int _i = 0; _i < 2; ++_i) \
;         __builtin_amdgcn_global_load_lds((const unsigned*)((const char*)(gbase) + (voff)[_i]), (PG8_LAS unsigned*)(lds + (bufoff) + ldsw + _i * 8192), 16, 0, 0); } while (0)
; #define PG8_LDA(dst, b, h) do { _Pragma("unroll") for (int m = 0; m < 4; ++m) _Pragma("unroll") for (int k = 0; k < 2; ++k) dst[m][k] = *(const PG8_LAS bf16x8*)(lds + PG8_SA(b, h) + aoff + m * 2048 + k * 1024); } while (0)
; #define PG8_LDB(dst, b, h) do { _Pragma("unroll") for (int n = 0; n < 2; ++n) _Pragma("unroll") for (int k = 0; k < 2; ++k) dst[n][k] = *(const PG8_LAS bf16x8*)(lds + PG8_SB(b, h) + boff + n * 2048 + k * 1024); } while (0)
; #define PG8_WAIT_V(n) asm volatile("s_waitcnt vmcnt(" #n ")" ::: "memory")
; #define PG8_WAIT_L(n) asm volatile("s_waitcnt lgkmcnt(" #n ")" ::: "memory")
; #define PG8_BAR __builtin_amdgcn_s_barrier()
; #define PG8_SCHED __builtin_amdgcn_sched_barrier(0)
; template <class Epi, class Sched, bool ALIGN_EPI = false, bool SP2 = false>
; __device__ __forceinline__ void gemm_phase(PG8_LAS unsigned char* lds, const Gemm g, const Sched& S, const Epi& E) {
;     ...
;         const char* nA = has_next ? (const char*)g.A + (size_t)nxt.pm * tstep : cA; const char* nB = has_next ? (const char*)g.Bt + (size_t)nxt.pn * tstep : cB;
;         for (int t = 0; t < nt; t += 2) {
;             const bool last = (t == nt - 2);
;             const char* a1 = cA + (size_t)(t + 1) * kstep;
;             const char* a2 = last ? nA : cA + (size_t)(t + 2) * kstep; const char* b2 = last ? nB : cB + (size_t)(t + 2) * kstep;
;             const char* a3 = a2 + kstep; const char* b3 = b2 + kstep;
;             if (last && has_next) S.a_ready(nxt);
;             if constexpr (SP2) {
;             PG8_LDB(B0, 0, 0); PG8_LDB(B1, 0, 1); PG8_SCHED; PG8_LDA(At, 0, 0); PG8_STAGE(PG8_SA(1, 1), a1 + hstep, voffA);
;             PG8_WAIT_V(8); PG8_WAIT_L(0); PG8_BAR; PG8_MMA(0, 0, At, B0); PG8_MMA(0, 1, At, B1); PG8_BAR; PG8_SCHED;
;     ...
; #pragma unroll
;         for (int a = 0; a < 2; ++a)
; #pragma unroll
;             for (int b = 0; b < 2; ++b)
; #pragma unroll
;                 for (int m = 0; m < 4; ++m)
; #pragma unroll
;                     for (int n = 0; n < 2; ++n) acc[a][b][m][n] = (f32x4){0.f, 0.f, 0.f, 0.f};
.LBB0_119:
	s_add_u32 s45, s28, 0x100
	s_addc_u32 s52, s29, 0
	s_mov_b32 s54, -2
	v_mov_b64_e32 v[2:3], 0
	v_mov_b64_e32 v[4:5], 0
	v_mov_b64_e32 v[6:7], 0
	v_mov_b64_e32 v[8:9], 0
	v_mov_b64_e32 v[10:11], 0
	v_mov_b64_e32 v[12:13], 0
	v_mov_b64_e32 v[14:15], 0
	v_mov_b64_e32 v[16:17], 0
	v_mov_b64_e32 v[18:19], 0
	v_mov_b64_e32 v[20:21], 0
	v_mov_b64_e32 v[22:23], 0
	v_mov_b64_e32 v[24:25], 0
	v_mov_b64_e32 v[26:27], 0
	v_mov_b64_e32 v[28:29], 0
	v_mov_b64_e32 v[30:31], 0
	v_mov_b64_e32 v[32:33], 0
	v_mov_b64_e32 v[34:35], 0
	v_mov_b64_e32 v[36:37], 0
	v_mov_b64_e32 v[38:39], 0
	v_mov_b64_e32 v[40:41], 0
	v_mov_b64_e32 v[42:43], 0
	v_mov_b64_e32 v[44:45], 0
	v_mov_b64_e32 v[46:47], 0
	v_mov_b64_e32 v[48:49], 0
	v_mov_b64_e32 v[50:51], 0
	v_mov_b64_e32 v[52:53], 0
	v_mov_b64_e32 v[54:55], 0
	v_mov_b64_e32 v[56:57], 0
	v_mov_b64_e32 v[58:59], 0
	v_mov_b64_e32 v[60:61], 0
	v_mov_b64_e32 v[62:63], 0
	v_mov_b64_e32 v[64:65], 0
	v_mov_b64_e32 v[66:67], 0
	v_mov_b64_e32 v[68:69], 0
	v_mov_b64_e32 v[70:71], 0
	v_mov_b64_e32 v[72:73], 0
	v_mov_b64_e32 v[74:75], 0
	v_mov_b64_e32 v[76:77], 0
	v_mov_b64_e32 v[78:79], 0
	v_mov_b64_e32 v[80:81], 0
	v_mov_b64_e32 v[82:83], 0
	v_mov_b64_e32 v[84:85], 0
	v_mov_b64_e32 v[86:87], 0
	v_mov_b64_e32 v[88:89], 0
	v_mov_b64_e32 v[90:91], 0
	v_mov_b64_e32 v[92:93], 0
	v_mov_b64_e32 v[94:95], 0
	v_mov_b64_e32 v[96:97], 0
	v_mov_b64_e32 v[98:99], 0
	v_mov_b64_e32 v[100:101], 0
	v_mov_b64_e32 v[102:103], 0
	v_mov_b64_e32 v[104:105], 0
	v_mov_b64_e32 v[106:107], 0
	v_mov_b64_e32 v[108:109], 0
	v_mov_b64_e32 v[110:111], 0
	v_mov_b64_e32 v[112:113], 0
	v_mov_b64_e32 v[114:115], 0
	v_mov_b64_e32 v[116:117], 0
	v_mov_b64_e32 v[118:119], 0
	v_mov_b64_e32 v[120:121], 0
	v_mov_b64_e32 v[122:123], 0
	v_mov_b64_e32 v[124:125], 0
	v_mov_b64_e32 v[126:127], 0
	v_mov_b64_e32 v[128:129], 0
	s_branch .Lz64_1
	s_nop 0
	s_nop 0
	s_nop 0
	s_nop 0
	s_nop 0
	s_nop 0
	s_nop 0
	s_nop 0
	s_nop 0
	s_nop 0
	s_nop 0
	s_nop 0
	s_nop 0
	s_nop 0
	s_nop 0
	s_nop 0
	s_nop 0
	s_nop 0
	s_nop 0
	s_nop 0
	s_nop 0
	s_nop 0
	s_nop 0
	s_nop 0
	s_nop 0
	s_nop 0
	s_nop 0
	s_nop 0
	s_nop 0
	s_nop 0
	s_nop 0
	s_nop 0
	s_nop 0
	s_nop 0
	s_nop 0
	s_nop 0
	s_nop 0
	s_nop 0
	s_nop 0
	s_nop 0
	s_nop 0
	s_nop 0
	s_nop 0
	s_nop 0
	s_nop 0
	s_nop 0
	s_nop 0
	s_nop 0
	s_nop 0
	s_nop 0
	s_nop 0
	s_nop 0
	s_nop 0
	s_nop 0
	s_nop 0
	s_nop 0
	s_nop 0
	s_nop 0
	s_nop 0
	s_nop 0
	s_nop 0
	s_nop 0
	s_nop 0
.Lz64_1:
.LBB0_120:
	s_add_u32 s28, s24, 0x100
	s_addc_u32 s29, s25, 0
	s_add_i32 s56, 0, 0x10000
	s_cmp_eq_u32 s54, 40
	s_cselect_b32 s35, s1, s29
	s_cselect_b32 s34, s0, s28
	s_cselect_b32 s31, s21, s52
	s_cselect_b32 s30, s20, s45
	s_add_i32 s57, 0, 0x14000
	v_add_u32_e32 v142, s56, v159
	v_add_u32_e32 v156, s57, v159
	ds_read_b128 v[130:133], v142
	ds_read_b128 v[134:137], v142 offset:1024
	ds_read_b128 v[138:141], v142 offset:2048
	ds_read_b128 v[142:145], v142 offset:3072
	ds_read_b128 v[152:155], v156
	ds_read_b128 v[162:165], v156 offset:1024
	ds_read_b128 v[166:169], v156 offset:2048
	ds_read_b128 v[178:181], v156 offset:3072
	v_lshl_add_u64 v[156:157], s[24:25], 0, v[150:151]
	s_add_i32 m0, s51, 0xc000
	ds_read_b128 v[182:185], v161
	ds_read_b128 v[186:189], v161 offset:1024
	ds_read_b128 v[190:193], v161 offset:2048
	ds_read_b128 v[194:197], v161 offset:3072
	ds_read_b128 v[198:201], v161 offset:4096
	ds_read_b128 v[202:205], v161 offset:5120
	ds_read_b128 v[206:209], v161 offset:6144
	ds_read_b128 v[224:227], v161 offset:7168
	global_load_lds_dwordx4 v[156:157], off
	v_lshl_add_u64 v[156:157], s[24:25], 0, v[148:149]
	s_add_i32 m0, s51, 0xe000
	s_nop 0
	global_load_lds_dwordx4 v[156:157], off
	s_waitcnt vmcnt(8)
	s_waitcnt lgkmcnt(0)
	s_barrier
	s_setprio 1
	s_waitcnt lgkmcnt(0)
	v_mfma_f32_16x16x32_bf16 v[126:129], v[130:133], v[182:185], v[126:129]
	v_mfma_f32_16x16x32_bf16 v[122:125], v[138:141], v[182:185], v[122:125]
	v_mfma_f32_16x16x32_bf16 v[118:121], v[130:133], v[190:193], v[118:121]
	v_mfma_f32_16x16x32_bf16 v[110:113], v[138:141], v[190:193], v[110:113]
	v_mfma_f32_16x16x32_bf16 v[102:105], v[130:133], v[198:201], v[102:105]
	v_mfma_f32_16x16x32_bf16 v[94:97], v[138:141], v[198:201], v[94:97]
	v_mfma_f32_16x16x32_bf16 v[86:89], v[130:133], v[206:209], v[86:89]
	v_mfma_f32_16x16x32_bf16 v[78:81], v[138:141], v[206:209], v[78:81]
	v_mfma_f32_16x16x32_bf16 v[126:129], v[134:137], v[186:189], v[126:129]
	v_mfma_f32_16x16x32_bf16 v[122:125], v[142:145], v[186:189], v[122:125]
	v_mfma_f32_16x16x32_bf16 v[118:121], v[134:137], v[194:197], v[118:121]
	v_mfma_f32_16x16x32_bf16 v[110:113], v[142:145], v[194:197], v[110:113]
	v_mfma_f32_16x16x32_bf16 v[102:105], v[134:137], v[202:205], v[102:105]
	v_mfma_f32_16x16x32_bf16 v[94:97], v[142:145], v[202:205], v[94:97]
	v_mfma_f32_16x16x32_bf16 v[86:89], v[134:137], v[224:227], v[86:89]
	v_mfma_f32_16x16x32_bf16 v[78:81], v[142:145], v[224:227], v[78:81]
	s_setprio 0
	s_setprio 1
	v_mfma_f32_16x16x32_bf16 v[114:117], v[152:155], v[182:185], v[114:117]
	v_mfma_f32_16x16x32_bf16 v[106:109], v[166:169], v[182:185], v[106:109]
	v_mfma_f32_16x16x32_bf16 v[98:101], v[152:155], v[190:193], v[98:101]
	v_mfma_f32_16x16x32_bf16 v[90:93], v[166:169], v[190:193], v[90:93]
	v_mfma_f32_16x16x32_bf16 v[82:85], v[152:155], v[198:201], v[82:85]
	v_mfma_f32_16x16x32_bf16 v[74:77], v[166:169], v[198:201], v[74:77]
	v_mfma_f32_16x16x32_bf16 v[70:73], v[152:155], v[206:209], v[70:73]
	v_mfma_f32_16x16x32_bf16 v[66:69], v[166:169], v[206:209], v[66:69]
	v_mfma_f32_16x16x32_bf16 v[114:117], v[162:165], v[186:189], v[114:117]
	v_mfma_f32_16x16x32_bf16 v[106:109], v[178:181], v[186:189], v[106:109]
	v_mfma_f32_16x16x32_bf16 v[98:101], v[162:165], v[194:197], v[98:101]
	v_mfma_f32_16x16x32_bf16 v[90:93], v[178:181], v[194:197], v[90:93]
	v_mfma_f32_16x16x32_bf16 v[82:85], v[162:165], v[202:205], v[82:85]
	v_mfma_f32_16x16x32_bf16 v[74:77], v[178:181], v[202:205], v[74:77]
	v_mfma_f32_16x16x32_bf16 v[70:73], v[162:165], v[224:227], v[70:73]
	v_mfma_f32_16x16x32_bf16 v[66:69], v[178:181], v[224:227], v[66:69]
	s_setprio 0
	s_barrier
; #define PG8_STAGE(bufoff, gbase, voff) do { _Pragma("unroll") for (int _i = 0; _i < 2; ++_i) \
;         __builtin_amdgcn_global_load_lds((const unsigned*)((const char*)(gbase) + (voff)[_i]), (PG8_LAS unsigned*)(lds + (bufoff) + ldsw + _i * 8192), 16, 0, 0); } while (0)
; #define PG8_LDA(dst, b, h) do { _Pragma("unroll") for (int m = 0; m < 4; ++m) _Pragma("unroll") for (int k = 0; k < 2; ++k) dst[m][k] = *(const PG8_LAS bf16x8*)(lds + PG8_SA(b, h) + aoff + m * 2048 + k * 1024); } while (0)
; #define PG8_LDB(dst, b, h) do { _Pragma("unroll") for (int n = 0; n < 2; ++n) _Pragma("unroll") for (int k = 0; k < 2; ++k) dst[n][k] = *(const PG8_LAS bf16x8*)(lds + PG8_SB(b, h) + boff + n * 2048 + k * 1024); } while (0)
; #define PG8_MMA(ai, bj, At, Bt) do { __builtin_amdgcn_s_setprio(1); _Pragma("unroll") for (int m = 0; m < 4; ++m) _Pragma("unroll") for (int n = 0; n < 2; ++n) _Pragma("unroll") for (int k = 0; k < 2; ++k) \
;         acc[ai][bj][m][n] = __builtin_amdgcn_mfma_f32_16x16x32_bf16(Bt[n][k], At[m][k], acc[ai][bj][m][n], 0, 0, 0); __builtin_amdgcn_s_setprio(0); } while (0)
; #define PG8_WAIT_V(n) asm volatile("s_waitcnt vmcnt(" #n ")" ::: "memory")
; #define PG8_WAIT_L(n) asm volatile("s_waitcnt lgkmcnt(" #n ")" ::: "memory")
; #define PG8_BAR __builtin_amdgcn_s_barrier()
; #define PG8_SCHED __builtin_amdgcn_sched_barrier(0)
; template <class Epi, class Sched, bool ALIGN_EPI = false, bool SP2 = false>
; __device__ __forceinline__ void gemm_phase(PG8_LAS unsigned char* lds, const Gemm g, const Sched& S, const Epi& E) {
;     ...
;             PG8_LDA(At, 0, 1); PG8_STAGE(PG8_SB(0, 0), b2, voffB); PG8_STAGE(PG8_SB(0, 1), b2 + hstep, voffB); PG8_STAGE(PG8_SA(0, 0), a2, voffA);
;             PG8_WAIT_V(8); PG8_WAIT_L(0); PG8_BAR; PG8_MMA(1, 0, At, B0); PG8_MMA(1, 1, At, B1); PG8_BAR; PG8_SCHED;
;             PG8_LDB(B0, 1, 0); PG8_LDB(B1, 1, 1); PG8_SCHED; PG8_LDA(At, 1, 0); PG8_STAGE(PG8_SA(0, 1), a2 + hstep, voffA);
	s_add_i32 s24, s56, s48
	v_lshl_add_u64 v[156:157], s[30:31], 0, v[0:1]
	s_mov_b32 m0, s24
	ds_read_b128 v[182:185], v161 offset:16384
	ds_read_b128 v[186:189], v161 offset:17408
	ds_read_b128 v[190:193], v161 offset:18432
	ds_read_b128 v[194:197], v161 offset:19456
	ds_read_b128 v[198:201], v161 offset:20480
	ds_read_b128 v[202:205], v161 offset:21504
	ds_read_b128 v[206:209], v161 offset:22528
	ds_read_b128 v[224:227], v161 offset:23552
	global_load_lds_dwordx4 v[156:157], off
	s_add_i32 m0, s24, 0x2000
	s_add_u32 s24, s30, 0xb0000
	v_lshl_add_u64 v[210:211], s[30:31], 0, v[146:147]
	s_addc_u32 s25, s31, 0
	s_add_i32 s56, s57, s48
	global_load_lds_dwordx4 v[210:211], off
	v_lshl_add_u64 v[228:229], s[24:25], 0, v[0:1]
	s_mov_b32 m0, s56
	v_lshl_add_u64 v[230:231], s[34:35], 0, v[146:147]
	global_load_lds_dwordx4 v[228:229], off
	v_lshl_add_u64 v[228:229], s[24:25], 0, v[146:147]
	s_add_i32 m0, s56, 0x2000
	s_nop 0
	global_load_lds_dwordx4 v[228:229], off
	v_lshl_add_u64 v[228:229], s[34:35], 0, v[0:1]
	s_mov_b32 m0, s51
	s_nop 0
	global_load_lds_dwordx4 v[228:229], off
	s_mov_b32 m0, s55
	s_nop 0
	global_load_lds_dwordx4 v[230:231], off
	s_waitcnt vmcnt(8)
	s_waitcnt lgkmcnt(0)
	s_barrier
	s_setprio 1
	s_waitcnt lgkmcnt(0)
	v_mfma_f32_16x16x32_bf16 v[62:65], v[130:133], v[182:185], v[62:65]
	v_mfma_f32_16x16x32_bf16 v[58:61], v[138:141], v[182:185], v[58:61]
	v_mfma_f32_16x16x32_bf16 v[54:57], v[130:133], v[190:193], v[54:57]
	v_mfma_f32_16x16x32_bf16 v[46:49], v[138:141], v[190:193], v[46:49]
	v_mfma_f32_16x16x32_bf16 v[38:41], v[130:133], v[198:201], v[38:41]
	v_mfma_f32_16x16x32_bf16 v[30:33], v[138:141], v[198:201], v[30:33]
	v_mfma_f32_16x16x32_bf16 v[22:25], v[130:133], v[206:209], v[22:25]
	v_mfma_f32_16x16x32_bf16 v[14:17], v[138:141], v[206:209], v[14:17]
	v_mfma_f32_16x16x32_bf16 v[62:65], v[134:137], v[186:189], v[62:65]
	v_mfma_f32_16x16x32_bf16 v[58:61], v[142:145], v[186:189], v[58:61]
	v_mfma_f32_16x16x32_bf16 v[54:57], v[134:137], v[194:197], v[54:57]
	v_mfma_f32_16x16x32_bf16 v[46:49], v[142:145], v[194:197], v[46:49]
	v_mfma_f32_16x16x32_bf16 v[38:41], v[134:137], v[202:205], v[38:41]
	v_mfma_f32_16x16x32_bf16 v[30:33], v[142:145], v[202:205], v[30:33]
	v_mfma_f32_16x16x32_bf16 v[22:25], v[134:137], v[224:227], v[22:25]
	v_mfma_f32_16x16x32_bf16 v[14:17], v[142:145], v[224:227], v[14:17]
	s_setprio 0
	s_setprio 1
	v_mfma_f32_16x16x32_bf16 v[50:53], v[152:155], v[182:185], v[50:53]
	v_mfma_f32_16x16x32_bf16 v[42:45], v[166:169], v[182:185], v[42:45]
	v_mfma_f32_16x16x32_bf16 v[34:37], v[152:155], v[190:193], v[34:37]
	v_mfma_f32_16x16x32_bf16 v[26:29], v[166:169], v[190:193], v[26:29]
	v_mfma_f32_16x16x32_bf16 v[18:21], v[152:155], v[198:201], v[18:21]
	v_mfma_f32_16x16x32_bf16 v[10:13], v[166:169], v[198:201], v[10:13]
	v_mfma_f32_16x16x32_bf16 v[6:9], v[152:155], v[206:209], v[6:9]
	v_mfma_f32_16x16x32_bf16 v[2:5], v[166:169], v[206:209], v[2:5]
	v_mfma_f32_16x16x32_bf16 v[50:53], v[162:165], v[186:189], v[50:53]
	v_mfma_f32_16x16x32_bf16 v[42:45], v[178:181], v[186:189], v[42:45]
	v_mfma_f32_16x16x32_bf16 v[34:37], v[162:165], v[194:197], v[34:37]
	v_mfma_f32_16x16x32_bf16 v[26:29], v[178:181], v[194:197], v[26:29]
	v_mfma_f32_16x16x32_bf16 v[18:21], v[162:165], v[202:205], v[18:21]
	v_mfma_f32_16x16x32_bf16 v[10:13], v[178:181], v[202:205], v[10:13]
	v_mfma_f32_16x16x32_bf16 v[6:9], v[162:165], v[224:227], v[6:9]
	v_mfma_f32_16x16x32_bf16 v[2:5], v[178:181], v[224:227], v[2:5]
	s_setprio 0
	s_barrier
	s_add_i32 s56, 0, 0x18000
	s_add_i32 s57, 0, 0x1c000
	v_add_u32_e32 v142, s56, v159
	v_add_u32_e32 v178, s57, v159
	ds_read_b128 v[130:133], v142
	ds_read_b128 v[134:137], v142 offset:1024
	ds_read_b128 v[138:141], v142 offset:2048
	ds_read_b128 v[142:145], v142 offset:3072
	ds_read_b128 v[152:155], v178
	ds_read_b128 v[162:165], v178 offset:1024
	ds_read_b128 v[166:169], v178 offset:2048
	ds_read_b128 v[178:181], v178 offset:3072
	s_add_u32 s24, s34, 0xb0000
	s_addc_u32 s25, s35, 0
	s_mov_b32 m0, s72
	v_lshl_add_u64 v[232:233], s[24:25], 0, v[0:1]
	ds_read_b128 v[182:185], v161 offset:32768
	ds_read_b128 v[186:189], v161 offset:33792
	ds_read_b128 v[190:193], v161 offset:34816
	ds_read_b128 v[194:197], v161 offset:35840
	ds_read_b128 v[198:201], v161 offset:36864
	ds_read_b128 v[202:205], v161 offset:37888
	ds_read_b128 v[206:209], v161 offset:38912
	ds_read_b128 v[224:227], v161 offset:39936
	global_load_lds_dwordx4 v[232:233], off
	v_lshl_add_u64 v[232:233], s[24:25], 0, v[146:147]
	s_mov_b32 m0, s73
	s_nop 0
	global_load_lds_dwordx4 v[232:233], off
	s_waitcnt vmcnt(8)
	s_waitcnt lgkmcnt(0)
	s_barrier
; #define PG8_STAGE(bufoff, gbase, voff) do { _Pragma("unroll") for (int _i = 0; _i < 2; ++_i) \
;         __builtin_amdgcn_global_load_lds((const unsigned*)((const char*)(gbase) + (voff)[_i]), (PG8_LAS unsigned*)(lds + (bufoff) + ldsw + _i * 8192), 16, 0, 0); } while (0)
; #define PG8_LDA(dst, b, h) do { _Pragma("unroll") for (int m = 0; m < 4; ++m) _Pragma("unroll") for (int k = 0; k < 2; ++k) dst[m][k] = *(const PG8_LAS bf16x8*)(lds + PG8_SA(b, h) + aoff + m * 2048 + k * 1024); } while (0)
; #define PG8_MMA(ai, bj, At, Bt) do { __builtin_amdgcn_s_setprio(1); _Pragma("unroll") for (int m = 0; m < 4; ++m) _Pragma("unroll") for (int n = 0; n < 2; ++n) _Pragma("unroll") for (int k = 0; k < 2; ++k) \
;         acc[ai][bj][m][n] = __builtin_amdgcn_mfma_f32_16x16x32_bf16(Bt[n][k], At[m][k], acc[ai][bj][m][n], 0, 0, 0); __builtin_amdgcn_s_setprio(0); } while (0)
; #define PG8_WAIT_V(n) asm volatile("s_waitcnt vmcnt(" #n ")" ::: "memory")
; #define PG8_WAIT_L(n) asm volatile("s_waitcnt lgkmcnt(" #n ")" ::: "memory")
; #define PG8_BAR __builtin_amdgcn_s_barrier()
; #define PG8_SCHED __builtin_amdgcn_sched_barrier(0)
; template <class Epi, class Sched, bool ALIGN_EPI = false, bool SP2 = false>
; __device__ __forceinline__ void gemm_phase(PG8_LAS unsigned char* lds, const Gemm g, const Sched& S, const Epi& E) {
;     ...
;             PG8_WAIT_V(8); PG8_WAIT_L(0); PG8_BAR; PG8_MMA(0, 0, At, B0); PG8_MMA(0, 1, At, B1); PG8_BAR; PG8_SCHED;
;             PG8_LDA(At, 1, 1); PG8_STAGE(PG8_SB(1, 0), b3, voffB); PG8_STAGE(PG8_SB(1, 1), b3 + hstep, voffB); PG8_STAGE(PG8_SA(1, 0), a3, voffA);
;             PG8_WAIT_V(8); PG8_WAIT_L(0); PG8_BAR; PG8_MMA(1, 0, At, B0); PG8_MMA(1, 1, At, B1); PG8_BAR; PG8_SCHED;
;     ...
;         if constexpr (ALIGN_EPI) { if (wr == 0) PG8_BAR; }
;         if constexpr (!Epi::AFTER_DRAIN) { E(acc, cur, wr, wc, fr, fq); S.done(cur); }
;         if (!has_next) break;
	s_setprio 1
	s_waitcnt lgkmcnt(0)
	v_mfma_f32_16x16x32_bf16 v[126:129], v[130:133], v[182:185], v[126:129]
	v_mfma_f32_16x16x32_bf16 v[122:125], v[138:141], v[182:185], v[122:125]
	v_mfma_f32_16x16x32_bf16 v[118:121], v[130:133], v[190:193], v[118:121]
	v_mfma_f32_16x16x32_bf16 v[110:113], v[138:141], v[190:193], v[110:113]
	v_mfma_f32_16x16x32_bf16 v[102:105], v[130:133], v[198:201], v[102:105]
	v_mfma_f32_16x16x32_bf16 v[94:97], v[138:141], v[198:201], v[94:97]
	v_mfma_f32_16x16x32_bf16 v[86:89], v[130:133], v[206:209], v[86:89]
	v_mfma_f32_16x16x32_bf16 v[78:81], v[138:141], v[206:209], v[78:81]
	v_mfma_f32_16x16x32_bf16 v[126:129], v[134:137], v[186:189], v[126:129]
	v_mfma_f32_16x16x32_bf16 v[122:125], v[142:145], v[186:189], v[122:125]
	v_mfma_f32_16x16x32_bf16 v[118:121], v[134:137], v[194:197], v[118:121]
	v_mfma_f32_16x16x32_bf16 v[110:113], v[142:145], v[194:197], v[110:113]
	v_mfma_f32_16x16x32_bf16 v[102:105], v[134:137], v[202:205], v[102:105]
	v_mfma_f32_16x16x32_bf16 v[94:97], v[142:145], v[202:205], v[94:97]
	v_mfma_f32_16x16x32_bf16 v[86:89], v[134:137], v[224:227], v[86:89]
	v_mfma_f32_16x16x32_bf16 v[78:81], v[142:145], v[224:227], v[78:81]
	s_setprio 0
	s_setprio 1
	v_mfma_f32_16x16x32_bf16 v[114:117], v[152:155], v[182:185], v[114:117]
	v_mfma_f32_16x16x32_bf16 v[106:109], v[166:169], v[182:185], v[106:109]
	v_mfma_f32_16x16x32_bf16 v[98:101], v[152:155], v[190:193], v[98:101]
	v_mfma_f32_16x16x32_bf16 v[90:93], v[166:169], v[190:193], v[90:93]
	v_mfma_f32_16x16x32_bf16 v[82:85], v[152:155], v[198:201], v[82:85]
	v_mfma_f32_16x16x32_bf16 v[74:77], v[166:169], v[198:201], v[74:77]
	v_mfma_f32_16x16x32_bf16 v[70:73], v[152:155], v[206:209], v[70:73]
	v_mfma_f32_16x16x32_bf16 v[66:69], v[166:169], v[206:209], v[66:69]
	v_mfma_f32_16x16x32_bf16 v[114:117], v[162:165], v[186:189], v[114:117]
	v_mfma_f32_16x16x32_bf16 v[106:109], v[178:181], v[186:189], v[106:109]
	v_mfma_f32_16x16x32_bf16 v[98:101], v[162:165], v[194:197], v[98:101]
	v_mfma_f32_16x16x32_bf16 v[90:93], v[178:181], v[194:197], v[90:93]
	v_mfma_f32_16x16x32_bf16 v[82:85], v[162:165], v[202:205], v[82:85]
	v_mfma_f32_16x16x32_bf16 v[74:77], v[178:181], v[202:205], v[74:77]
	v_mfma_f32_16x16x32_bf16 v[70:73], v[162:165], v[224:227], v[70:73]
	v_mfma_f32_16x16x32_bf16 v[66:69], v[178:181], v[224:227], v[66:69]
	s_setprio 0
	s_barrier
	s_add_i32 s24, s56, s48
	v_lshl_add_u64 v[156:157], v[156:157], 0, s[88:89]
	s_mov_b32 m0, s24
	ds_read_b128 v[182:185], v161 offset:49152
	ds_read_b128 v[186:189], v161 offset:50176
	ds_read_b128 v[190:193], v161 offset:51200
	ds_read_b128 v[194:197], v161 offset:52224
	ds_read_b128 v[198:201], v161 offset:53248
	ds_read_b128 v[202:205], v161 offset:54272
	ds_read_b128 v[206:209], v161 offset:55296
	ds_read_b128 v[224:227], v161 offset:56320
	global_load_lds_dwordx4 v[156:157], off
	s_add_i32 m0, s24, 0x2000
	s_add_u32 s24, s30, 0xb0080
	v_lshl_add_u64 v[156:157], v[210:211], 0, s[88:89]
	s_addc_u32 s25, s31, 0
	s_add_i32 s30, s57, s48
	global_load_lds_dwordx4 v[156:157], off
	v_lshl_add_u64 v[156:157], s[24:25], 0, v[0:1]
	s_mov_b32 m0, s30
	s_nop 0
	global_load_lds_dwordx4 v[156:157], off
	v_lshl_add_u64 v[156:157], s[24:25], 0, v[146:147]
	s_add_i32 m0, s30, 0x2000
	s_nop 0
	global_load_lds_dwordx4 v[156:157], off
	v_lshl_add_u64 v[156:157], v[228:229], 0, s[88:89]
	s_mov_b32 m0, s76
	s_nop 0
	global_load_lds_dwordx4 v[156:157], off
	v_lshl_add_u64 v[156:157], v[230:231], 0, s[88:89]
	s_mov_b32 m0, s77
	s_nop 0
	global_load_lds_dwordx4 v[156:157], off
	s_waitcnt vmcnt(8)
	s_waitcnt lgkmcnt(0)
	s_barrier
	s_setprio 1
	s_waitcnt lgkmcnt(0)
	v_mfma_f32_16x16x32_bf16 v[62:65], v[130:133], v[182:185], v[62:65]
	v_mfma_f32_16x16x32_bf16 v[58:61], v[138:141], v[182:185], v[58:61]
	v_mfma_f32_16x16x32_bf16 v[54:57], v[130:133], v[190:193], v[54:57]
	v_mfma_f32_16x16x32_bf16 v[46:49], v[138:141], v[190:193], v[46:49]
	v_mfma_f32_16x16x32_bf16 v[38:41], v[130:133], v[198:201], v[38:41]
	v_mfma_f32_16x16x32_bf16 v[30:33], v[138:141], v[198:201], v[30:33]
	v_mfma_f32_16x16x32_bf16 v[22:25], v[130:133], v[206:209], v[22:25]
	v_mfma_f32_16x16x32_bf16 v[14:17], v[138:141], v[206:209], v[14:17]
	v_mfma_f32_16x16x32_bf16 v[62:65], v[134:137], v[186:189], v[62:65]
	v_mfma_f32_16x16x32_bf16 v[58:61], v[142:145], v[186:189], v[58:61]
	v_mfma_f32_16x16x32_bf16 v[54:57], v[134:137], v[194:197], v[54:57]
	v_mfma_f32_16x16x32_bf16 v[46:49], v[142:145], v[194:197], v[46:49]
	v_mfma_f32_16x16x32_bf16 v[38:41], v[134:137], v[202:205], v[38:41]
	v_mfma_f32_16x16x32_bf16 v[30:33], v[142:145], v[202:205], v[30:33]
	v_mfma_f32_16x16x32_bf16 v[22:25], v[134:137], v[224:227], v[22:25]
	v_mfma_f32_16x16x32_bf16 v[14:17], v[142:145], v[224:227], v[14:17]
	s_setprio 0
	s_setprio 1
	v_mfma_f32_16x16x32_bf16 v[50:53], v[152:155], v[182:185], v[50:53]
	v_mfma_f32_16x16x32_bf16 v[42:45], v[166:169], v[182:185], v[42:45]
	v_mfma_f32_16x16x32_bf16 v[34:37], v[152:155], v[190:193], v[34:37]
	v_mfma_f32_16x16x32_bf16 v[26:29], v[166:169], v[190:193], v[26:29]
	v_mfma_f32_16x16x32_bf16 v[18:21], v[152:155], v[198:201], v[18:21]
	v_mfma_f32_16x16x32_bf16 v[10:13], v[166:169], v[198:201], v[10:13]
	v_mfma_f32_16x16x32_bf16 v[6:9], v[152:155], v[206:209], v[6:9]
	v_mfma_f32_16x16x32_bf16 v[2:5], v[166:169], v[206:209], v[2:5]
	v_mfma_f32_16x16x32_bf16 v[50:53], v[162:165], v[186:189], v[50:53]
	v_mfma_f32_16x16x32_bf16 v[42:45], v[178:181], v[186:189], v[42:45]
	v_mfma_f32_16x16x32_bf16 v[34:37], v[162:165], v[194:197], v[34:37]
	v_mfma_f32_16x16x32_bf16 v[26:29], v[178:181], v[194:197], v[26:29]
	v_mfma_f32_16x16x32_bf16 v[18:21], v[162:165], v[202:205], v[18:21]
	v_mfma_f32_16x16x32_bf16 v[10:13], v[178:181], v[202:205], v[10:13]
	v_mfma_f32_16x16x32_bf16 v[6:9], v[162:165], v[224:227], v[6:9]
	v_mfma_f32_16x16x32_bf16 v[2:5], v[178:181], v[224:227], v[2:5]
	s_setprio 0
	s_barrier
	s_add_i32 s54, s54, 2
	s_add_u32 s45, s45, 0x100
	s_addc_u32 s52, s52, 0
	s_cmp_gt_u32 s54, 41
	s_mov_b64 s[24:25], s[28:29]
	s_cbranch_scc0 .LBB0_120
	s_and_b64 vcc, exec, s[14:15]
	s_cbranch_vccz .LBB0_123
	s_barrier

; #define PG8_STAGE(bufoff, gbase, voff) do { _Pragma("unroll") for (int _i = 0; _i < 2; ++_i) \
;         __builtin_amdgcn_global_load_lds((const unsigned*)((const char*)(gbase) + (voff)[_i]), (PG8_LAS unsigned*)(lds + (bufoff) + ldsw + _i * 8192), 16, 0, 0); } while (0)
; #define PG8_LDA(dst, b, h) do { _Pragma("unroll") for (int m = 0; m < 4; ++m) _Pragma("unroll") for (int k = 0; k < 2; ++k) dst[m][k] = *(const PG8_LAS bf16x8*)(lds + PG8_SA(b, h) + aoff + m * 2048 + k * 1024); } while (0)
; #define PG8_LDB(dst, b, h) do { _Pragma("unroll") for (int n = 0; n < 2; ++n) _Pragma("unroll") for (int k = 0; k < 2; ++k) dst[n][k] = *(const PG8_LAS bf16x8*)(lds + PG8_SB(b, h) + boff + n * 2048 + k * 1024); } while (0)
; #define PG8_WAIT_V(n) asm volatile("s_waitcnt vmcnt(" #n ")" ::: "memory")
; #define PG8_WAIT_L(n) asm volatile("s_waitcnt lgkmcnt(" #n ")" ::: "memory")
; #define PG8_BAR __builtin_amdgcn_s_barrier()
; #define PG8_SCHED __builtin_amdgcn_sched_barrier(0)
; template <class Epi, class Sched, bool ALIGN_EPI = false, bool SP2 = false>
; __device__ __forceinline__ void gemm_phase(PG8_LAS unsigned char* lds, const Gemm g, const Sched& S, const Epi& E) {
;     ...
;         const char* nA = has_next ? (const char*)g.A + (size_t)nxt.pm * tstep : cA; const char* nB = has_next ? (const char*)g.Bt + (size_t)nxt.pn * tstep : cB;
;         for (int t = 0; t < nt; t += 2) {
;             const bool last = (t == nt - 2);
;             const char* a1 = cA + (size_t)(t + 1) * kstep;
;             const char* a2 = last ? nA : cA + (size_t)(t + 2) * kstep; const char* b2 = last ? nB : cB + (size_t)(t + 2) * kstep;
;             const char* a3 = a2 + kstep; const char* b3 = b2 + kstep;
;             if (last && has_next) S.a_ready(nxt);
;             if constexpr (SP2) {
;             PG8_LDB(B0, 0, 0); PG8_LDB(B1, 0, 1); PG8_SCHED; PG8_LDA(At, 0, 0); PG8_STAGE(PG8_SA(1, 1), a1 + hstep, voffA);
;             PG8_WAIT_V(8); PG8_WAIT_L(0); PG8_BAR; PG8_MMA(0, 0, At, B0); PG8_MMA(0, 1, At, B1); PG8_BAR; PG8_SCHED;
;     ...
; #pragma unroll
;         for (int a = 0; a < 2; ++a)
; #pragma unroll
;             for (int b = 0; b < 2; ++b)
; #pragma unroll
;                 for (int m = 0; m < 4; ++m)
; #pragma unroll
;                     for (int n = 0; n < 2; ++n) acc[a][b][m][n] = (f32x4){0.f, 0.f, 0.f, 0.f};
.LBB0_152:
	s_ashr_i32 s13, s12, 31
	s_lshl_b64 s[14:15], s[12:13], 19
	s_add_u32 s14, s26, s14
	s_addc_u32 s15, s27, s15
	s_and_b64 s[20:21], s[6:7], exec
	s_cselect_b32 s13, s15, s25
	s_cselect_b32 s78, s14, s24
	s_ashr_i32 s11, s10, 31
	s_lshl_b64 s[20:21], s[10:11], 19
	s_add_u32 s20, s39, s20
	s_addc_u32 s21, s41, s21
	s_and_b64 s[30:31], s[6:7], exec
	s_cselect_b32 s11, s21, s29
	s_cselect_b32 s45, s20, s28
	s_add_u32 s52, s28, 0x100
	s_addc_u32 s54, s29, 0
	s_mov_b32 s56, -2
	v_mov_b64_e32 v[2:3], 0
	v_mov_b64_e32 v[4:5], 0
	v_mov_b64_e32 v[6:7], 0
	v_mov_b64_e32 v[8:9], 0
	v_mov_b64_e32 v[10:11], 0
	v_mov_b64_e32 v[12:13], 0
	v_mov_b64_e32 v[14:15], 0
	v_mov_b64_e32 v[16:17], 0
	v_mov_b64_e32 v[18:19], 0
	v_mov_b64_e32 v[20:21], 0
	v_mov_b64_e32 v[22:23], 0
	v_mov_b64_e32 v[24:25], 0
	v_mov_b64_e32 v[26:27], 0
	v_mov_b64_e32 v[28:29], 0
	v_mov_b64_e32 v[30:31], 0
	v_mov_b64_e32 v[32:33], 0
	v_mov_b64_e32 v[34:35], 0
	v_mov_b64_e32 v[36:37], 0
	v_mov_b64_e32 v[38:39], 0
	v_mov_b64_e32 v[40:41], 0
	v_mov_b64_e32 v[42:43], 0
	v_mov_b64_e32 v[44:45], 0
	v_mov_b64_e32 v[46:47], 0
	v_mov_b64_e32 v[48:49], 0
	v_mov_b64_e32 v[50:51], 0
	v_mov_b64_e32 v[52:53], 0
	v_mov_b64_e32 v[54:55], 0
	v_mov_b64_e32 v[56:57], 0
	v_mov_b64_e32 v[58:59], 0
	v_mov_b64_e32 v[60:61], 0
	v_mov_b64_e32 v[62:63], 0
	v_mov_b64_e32 v[64:65], 0
	v_mov_b64_e32 v[66:67], 0
	v_mov_b64_e32 v[68:69], 0
	v_mov_b64_e32 v[70:71], 0
	v_mov_b64_e32 v[72:73], 0
	v_mov_b64_e32 v[74:75], 0
	v_mov_b64_e32 v[76:77], 0
	v_mov_b64_e32 v[78:79], 0
	v_mov_b64_e32 v[80:81], 0
	v_mov_b64_e32 v[82:83], 0
	v_mov_b64_e32 v[84:85], 0
	v_mov_b64_e32 v[86:87], 0
	v_mov_b64_e32 v[88:89], 0
	v_mov_b64_e32 v[90:91], 0
	v_mov_b64_e32 v[92:93], 0
	v_mov_b64_e32 v[94:95], 0
	v_mov_b64_e32 v[96:97], 0
	v_mov_b64_e32 v[98:99], 0
	v_mov_b64_e32 v[100:101], 0
	v_mov_b64_e32 v[102:103], 0
	v_mov_b64_e32 v[104:105], 0
	v_mov_b64_e32 v[106:107], 0
	v_mov_b64_e32 v[108:109], 0
	v_mov_b64_e32 v[110:111], 0
	v_mov_b64_e32 v[112:113], 0
	v_mov_b64_e32 v[114:115], 0
	v_mov_b64_e32 v[116:117], 0
	v_mov_b64_e32 v[118:119], 0
	v_mov_b64_e32 v[120:121], 0
	v_mov_b64_e32 v[122:123], 0
	v_mov_b64_e32 v[124:125], 0
	v_mov_b64_e32 v[126:127], 0
	v_mov_b64_e32 v[128:129], 0
	s_branch .Lz64_2
	s_nop 0
	s_nop 0
	s_nop 0
	s_nop 0
	s_nop 0
	s_nop 0
	s_nop 0
	s_nop 0
	s_nop 0
	s_nop 0
	s_nop 0
	s_nop 0
	s_nop 0
	s_nop 0
	s_nop 0
	s_nop 0
	s_nop 0
	s_nop 0
	s_nop 0
	s_nop 0
	s_nop 0
	s_nop 0
	s_nop 0
	s_nop 0
	s_nop 0
	s_nop 0
	s_nop 0
	s_nop 0
	s_nop 0
	s_nop 0
	s_nop 0
	s_nop 0
	s_nop 0
	s_nop 0
	s_nop 0
	s_nop 0
	s_nop 0
	s_nop 0
	s_nop 0
	s_nop 0
	s_nop 0
	s_nop 0
	s_nop 0
	s_nop 0
	s_nop 0
	s_nop 0
	s_nop 0
	s_nop 0
	s_nop 0
	s_nop 0
	s_nop 0
	s_nop 0
	s_nop 0
	s_nop 0
	s_nop 0
	s_nop 0
	s_nop 0
	s_nop 0
	s_nop 0
	s_nop 0
	s_nop 0
	s_nop 0
	s_nop 0
.Lz64_2:
.LBB0_153:
	s_add_u32 s28, s24, 0x100
	s_addc_u32 s29, s25, 0
	s_add_i32 s57, 0, 0x10000
	s_cmp_eq_u32 s56, 12
	s_cselect_b32 s35, s13, s29
	s_cselect_b32 s34, s78, s28
	s_cselect_b32 s31, s11, s54
	s_cselect_b32 s30, s45, s52
	s_add_i32 s58, 0, 0x14000
	v_add_u32_e32 v142, s57, v159
	v_add_u32_e32 v156, s58, v159
	ds_read_b128 v[130:133], v142
	ds_read_b128 v[134:137], v142 offset:1024
	ds_read_b128 v[138:141], v142 offset:2048
	ds_read_b128 v[142:145], v142 offset:3072
	ds_read_b128 v[152:155], v156
	ds_read_b128 v[162:165], v156 offset:1024
	ds_read_b128 v[166:169], v156 offset:2048
	ds_read_b128 v[178:181], v156 offset:3072
	v_lshl_add_u64 v[156:157], s[24:25], 0, v[150:151]
	s_add_i32 m0, s23, 0xc000
	ds_read_b128 v[182:185], v161
	ds_read_b128 v[186:189], v161 offset:1024
	ds_read_b128 v[190:193], v161 offset:2048
	ds_read_b128 v[194:197], v161 offset:3072
	ds_read_b128 v[198:201], v161 offset:4096
	ds_read_b128 v[202:205], v161 offset:5120
	ds_read_b128 v[206:209], v161 offset:6144
	ds_read_b128 v[224:227], v161 offset:7168
	global_load_lds_dwordx4 v[156:157], off
	v_lshl_add_u64 v[156:157], s[24:25], 0, v[148:149]
	s_add_i32 m0, s23, 0xe000
	s_nop 0
	global_load_lds_dwordx4 v[156:157], off
	s_waitcnt vmcnt(8)
	s_waitcnt lgkmcnt(0)
	s_barrier
	s_setprio 1
	s_waitcnt lgkmcnt(0)
	v_mfma_f32_16x16x32_bf16 v[126:129], v[130:133], v[182:185], v[126:129]
	v_mfma_f32_16x16x32_bf16 v[122:125], v[138:141], v[182:185], v[122:125]
	v_mfma_f32_16x16x32_bf16 v[118:121], v[130:133], v[190:193], v[118:121]
	v_mfma_f32_16x16x32_bf16 v[110:113], v[138:141], v[190:193], v[110:113]
	v_mfma_f32_16x16x32_bf16 v[102:105], v[130:133], v[198:201], v[102:105]
	v_mfma_f32_16x16x32_bf16 v[94:97], v[138:141], v[198:201], v[94:97]
	v_mfma_f32_16x16x32_bf16 v[86:89], v[130:133], v[206:209], v[86:89]
	v_mfma_f32_16x16x32_bf16 v[78:81], v[138:141], v[206:209], v[78:81]
	v_mfma_f32_16x16x32_bf16 v[126:129], v[134:137], v[186:189], v[126:129]
	v_mfma_f32_16x16x32_bf16 v[122:125], v[142:145], v[186:189], v[122:125]
	v_mfma_f32_16x16x32_bf16 v[118:121], v[134:137], v[194:197], v[118:121]
	v_mfma_f32_16x16x32_bf16 v[110:113], v[142:145], v[194:197], v[110:113]
	v_mfma_f32_16x16x32_bf16 v[102:105], v[134:137], v[202:205], v[102:105]
	v_mfma_f32_16x16x32_bf16 v[94:97], v[142:145], v[202:205], v[94:97]
	v_mfma_f32_16x16x32_bf16 v[86:89], v[134:137], v[224:227], v[86:89]
	v_mfma_f32_16x16x32_bf16 v[78:81], v[142:145], v[224:227], v[78:81]
	s_setprio 0
	s_setprio 1
	v_mfma_f32_16x16x32_bf16 v[114:117], v[152:155], v[182:185], v[114:117]
	v_mfma_f32_16x16x32_bf16 v[106:109], v[166:169], v[182:185], v[106:109]
	v_mfma_f32_16x16x32_bf16 v[98:101], v[152:155], v[190:193], v[98:101]
	v_mfma_f32_16x16x32_bf16 v[90:93], v[166:169], v[190:193], v[90:93]
	v_mfma_f32_16x16x32_bf16 v[82:85], v[152:155], v[198:201], v[82:85]
	v_mfma_f32_16x16x32_bf16 v[74:77], v[166:169], v[198:201], v[74:77]
	v_mfma_f32_16x16x32_bf16 v[70:73], v[152:155], v[206:209], v[70:73]
	v_mfma_f32_16x16x32_bf16 v[66:69], v[166:169], v[206:209], v[66:69]
	v_mfma_f32_16x16x32_bf16 v[114:117], v[162:165], v[186:189], v[114:117]
	v_mfma_f32_16x16x32_bf16 v[106:109], v[178:181], v[186:189], v[106:109]
	v_mfma_f32_16x16x32_bf16 v[98:101], v[162:165], v[194:197], v[98:101]
	v_mfma_f32_16x16x32_bf16 v[90:93], v[178:181], v[194:197], v[90:93]
	v_mfma_f32_16x16x32_bf16 v[82:85], v[162:165], v[202:205], v[82:85]
	v_mfma_f32_16x16x32_bf16 v[74:77], v[178:181], v[202:205], v[74:77]
	v_mfma_f32_16x16x32_bf16 v[70:73], v[162:165], v[224:227], v[70:73]
	v_mfma_f32_16x16x32_bf16 v[66:69], v[178:181], v[224:227], v[66:69]
	s_setprio 0
	s_barrier
; #define PG8_STAGE(bufoff, gbase, voff) do { _Pragma("unroll") for (int _i = 0; _i < 2; ++_i) \
;         __builtin_amdgcn_global_load_lds((const unsigned*)((const char*)(gbase) + (voff)[_i]), (PG8_LAS unsigned*)(lds + (bufoff) + ldsw + _i * 8192), 16, 0, 0); } while (0)
; #define PG8_LDA(dst, b, h) do { _Pragma("unroll") for (int m = 0; m < 4; ++m) _Pragma("unroll") for (int k = 0; k < 2; ++k) dst[m][k] = *(const PG8_LAS bf16x8*)(lds + PG8_SA(b, h) + aoff + m * 2048 + k * 1024); } while (0)
; #define PG8_LDB(dst, b, h) do { _Pragma("unroll") for (int n = 0; n < 2; ++n) _Pragma("unroll") for (int k = 0; k < 2; ++k) dst[n][k] = *(const PG8_LAS bf16x8*)(lds + PG8_SB(b, h) + boff + n * 2048 + k * 1024); } while (0)
; #define PG8_MMA(ai, bj, At, Bt) do { __builtin_amdgcn_s_setprio(1); _Pragma("unroll") for (int m = 0; m < 4; ++m) _Pragma("unroll") for (int n = 0; n < 2; ++n) _Pragma("unroll") for (int k = 0; k < 2; ++k) \
;         acc[ai][bj][m][n] = __builtin_amdgcn_mfma_f32_16x16x32_bf16(Bt[n][k], At[m][k], acc[ai][bj][m][n], 0, 0, 0); __builtin_amdgcn_s_setprio(0); } while (0)
; #define PG8_WAIT_V(n) asm volatile("s_waitcnt vmcnt(" #n ")" ::: "memory")
; #define PG8_WAIT_L(n) asm volatile("s_waitcnt lgkmcnt(" #n ")" ::: "memory")
; #define PG8_BAR __builtin_amdgcn_s_barrier()
; #define PG8_SCHED __builtin_amdgcn_sched_barrier(0)
; template <class Epi, class Sched, bool ALIGN_EPI = false, bool SP2 = false>
; __device__ __forceinline__ void gemm_phase(PG8_LAS unsigned char* lds, const Gemm g, const Sched& S, const Epi& E) {
;     ...
;             PG8_LDA(At, 0, 1); PG8_STAGE(PG8_SB(0, 0), b2, voffB); PG8_STAGE(PG8_SB(0, 1), b2 + hstep, voffB); PG8_STAGE(PG8_SA(0, 0), a2, voffA);
;             PG8_WAIT_V(8); PG8_WAIT_L(0); PG8_BAR; PG8_MMA(1, 0, At, B0); PG8_MMA(1, 1, At, B1); PG8_BAR; PG8_SCHED;
;             PG8_LDB(B0, 1, 0); PG8_LDB(B1, 1, 1); PG8_SCHED; PG8_LDA(At, 1, 0); PG8_STAGE(PG8_SA(0, 1), a2 + hstep, voffA);
	s_add_i32 s24, s57, s43
	v_lshl_add_u64 v[156:157], s[30:31], 0, v[0:1]
	s_mov_b32 m0, s24
	ds_read_b128 v[182:185], v161 offset:16384
	ds_read_b128 v[186:189], v161 offset:17408
	ds_read_b128 v[190:193], v161 offset:18432
	ds_read_b128 v[194:197], v161 offset:19456
	ds_read_b128 v[198:201], v161 offset:20480
	ds_read_b128 v[202:205], v161 offset:21504
	ds_read_b128 v[206:209], v161 offset:22528
	ds_read_b128 v[224:227], v161 offset:23552
	global_load_lds_dwordx4 v[156:157], off
	s_add_i32 m0, s24, 0x2000
	s_add_u32 s24, s30, 0x40000
	v_lshl_add_u64 v[210:211], s[30:31], 0, v[146:147]
	s_addc_u32 s25, s31, 0
	s_add_i32 s57, s58, s43
	global_load_lds_dwordx4 v[210:211], off
	v_lshl_add_u64 v[228:229], s[24:25], 0, v[0:1]
	s_mov_b32 m0, s57
	v_lshl_add_u64 v[230:231], s[34:35], 0, v[146:147]
	global_load_lds_dwordx4 v[228:229], off
	v_lshl_add_u64 v[228:229], s[24:25], 0, v[146:147]
	s_add_i32 m0, s57, 0x2000
	s_nop 0
	global_load_lds_dwordx4 v[228:229], off
	v_lshl_add_u64 v[228:229], s[34:35], 0, v[0:1]
	s_mov_b32 m0, s23
	s_nop 0
	global_load_lds_dwordx4 v[228:229], off
	s_mov_b32 m0, s47
	s_nop 0
	global_load_lds_dwordx4 v[230:231], off
	s_waitcnt vmcnt(8)
	s_waitcnt lgkmcnt(0)
	s_barrier
	s_setprio 1
	s_waitcnt lgkmcnt(0)
	v_mfma_f32_16x16x32_bf16 v[62:65], v[130:133], v[182:185], v[62:65]
	v_mfma_f32_16x16x32_bf16 v[58:61], v[138:141], v[182:185], v[58:61]
	v_mfma_f32_16x16x32_bf16 v[54:57], v[130:133], v[190:193], v[54:57]
	v_mfma_f32_16x16x32_bf16 v[46:49], v[138:141], v[190:193], v[46:49]
	v_mfma_f32_16x16x32_bf16 v[38:41], v[130:133], v[198:201], v[38:41]
	v_mfma_f32_16x16x32_bf16 v[30:33], v[138:141], v[198:201], v[30:33]
	v_mfma_f32_16x16x32_bf16 v[22:25], v[130:133], v[206:209], v[22:25]
	v_mfma_f32_16x16x32_bf16 v[14:17], v[138:141], v[206:209], v[14:17]
	v_mfma_f32_16x16x32_bf16 v[62:65], v[134:137], v[186:189], v[62:65]
	v_mfma_f32_16x16x32_bf16 v[58:61], v[142:145], v[186:189], v[58:61]
	v_mfma_f32_16x16x32_bf16 v[54:57], v[134:137], v[194:197], v[54:57]
	v_mfma_f32_16x16x32_bf16 v[46:49], v[142:145], v[194:197], v[46:49]
	v_mfma_f32_16x16x32_bf16 v[38:41], v[134:137], v[202:205], v[38:41]
	v_mfma_f32_16x16x32_bf16 v[30:33], v[142:145], v[202:205], v[30:33]
	v_mfma_f32_16x16x32_bf16 v[22:25], v[134:137], v[224:227], v[22:25]
	v_mfma_f32_16x16x32_bf16 v[14:17], v[142:145], v[224:227], v[14:17]
	s_setprio 0
	s_setprio 1
	v_mfma_f32_16x16x32_bf16 v[50:53], v[152:155], v[182:185], v[50:53]
	v_mfma_f32_16x16x32_bf16 v[42:45], v[166:169], v[182:185], v[42:45]
	v_mfma_f32_16x16x32_bf16 v[34:37], v[152:155], v[190:193], v[34:37]
	v_mfma_f32_16x16x32_bf16 v[26:29], v[166:169], v[190:193], v[26:29]
	v_mfma_f32_16x16x32_bf16 v[18:21], v[152:155], v[198:201], v[18:21]
	v_mfma_f32_16x16x32_bf16 v[10:13], v[166:169], v[198:201], v[10:13]
	v_mfma_f32_16x16x32_bf16 v[6:9], v[152:155], v[206:209], v[6:9]
	v_mfma_f32_16x16x32_bf16 v[2:5], v[166:169], v[206:209], v[2:5]
	v_mfma_f32_16x16x32_bf16 v[50:53], v[162:165], v[186:189], v[50:53]
	v_mfma_f32_16x16x32_bf16 v[42:45], v[178:181], v[186:189], v[42:45]
	v_mfma_f32_16x16x32_bf16 v[34:37], v[162:165], v[194:197], v[34:37]
	v_mfma_f32_16x16x32_bf16 v[26:29], v[178:181], v[194:197], v[26:29]
	v_mfma_f32_16x16x32_bf16 v[18:21], v[162:165], v[202:205], v[18:21]
	v_mfma_f32_16x16x32_bf16 v[10:13], v[178:181], v[202:205], v[10:13]
	v_mfma_f32_16x16x32_bf16 v[6:9], v[162:165], v[224:227], v[6:9]
	v_mfma_f32_16x16x32_bf16 v[2:5], v[178:181], v[224:227], v[2:5]
	s_setprio 0
	s_barrier
	s_add_i32 s57, 0, 0x18000
	s_add_i32 s58, 0, 0x1c000
	v_add_u32_e32 v142, s57, v159
	v_add_u32_e32 v178, s58, v159
	ds_read_b128 v[130:133], v142
	ds_read_b128 v[134:137], v142 offset:1024
	ds_read_b128 v[138:141], v142 offset:2048
	ds_read_b128 v[142:145], v142 offset:3072
	ds_read_b128 v[152:155], v178
	ds_read_b128 v[162:165], v178 offset:1024
	ds_read_b128 v[166:169], v178 offset:2048
	ds_read_b128 v[178:181], v178 offset:3072
	s_add_u32 s24, s34, 0x40000
	s_addc_u32 s25, s35, 0
	s_mov_b32 m0, s48
	v_lshl_add_u64 v[232:233], s[24:25], 0, v[0:1]
	ds_read_b128 v[182:185], v161 offset:32768
	ds_read_b128 v[186:189], v161 offset:33792
	ds_read_b128 v[190:193], v161 offset:34816
	ds_read_b128 v[194:197], v161 offset:35840
	ds_read_b128 v[198:201], v161 offset:36864
	ds_read_b128 v[202:205], v161 offset:37888
	ds_read_b128 v[206:209], v161 offset:38912
	ds_read_b128 v[224:227], v161 offset:39936
	global_load_lds_dwordx4 v[232:233], off
	v_lshl_add_u64 v[232:233], s[24:25], 0, v[146:147]
	s_mov_b32 m0, s51
	s_nop 0
	global_load_lds_dwordx4 v[232:233], off
	s_waitcnt vmcnt(8)
	s_waitcnt lgkmcnt(0)
	s_barrier
; #define PG8_STAGE(bufoff, gbase, voff) do { _Pragma("unroll") for (int _i = 0; _i < 2; ++_i) \
;         __builtin_amdgcn_global_load_lds((const unsigned*)((const char*)(gbase) + (voff)[_i]), (PG8_LAS unsigned*)(lds + (bufoff) + ldsw + _i * 8192), 16, 0, 0); } while (0)
; #define PG8_LDA(dst, b, h) do { _Pragma("unroll") for (int m = 0; m < 4; ++m) _Pragma("unroll") for (int k = 0; k < 2; ++k) dst[m][k] = *(const PG8_LAS bf16x8*)(lds + PG8_SA(b, h) + aoff + m * 2048 + k * 1024); } while (0)
; #define PG8_MMA(ai, bj, At, Bt) do { __builtin_amdgcn_s_setprio(1); _Pragma("unroll") for (int m = 0; m < 4; ++m) _Pragma("unroll") for (int n = 0; n < 2; ++n) _Pragma("unroll") for (int k = 0; k < 2; ++k) \
;         acc[ai][bj][m][n] = __builtin_amdgcn_mfma_f32_16x16x32_bf16(Bt[n][k], At[m][k], acc[ai][bj][m][n], 0, 0, 0); __builtin_amdgcn_s_setprio(0); } while (0)
; #define PG8_WAIT_V(n) asm volatile("s_waitcnt vmcnt(" #n ")" ::: "memory")
; #define PG8_WAIT_L(n) asm volatile("s_waitcnt lgkmcnt(" #n ")" ::: "memory")
; #define PG8_BAR __builtin_amdgcn_s_barrier()
; #define PG8_SCHED __builtin_amdgcn_sched_barrier(0)
; template <class Epi, class Sched, bool ALIGN_EPI = false, bool SP2 = false>
; __device__ __forceinline__ void gemm_phase(PG8_LAS unsigned char* lds, const Gemm g, const Sched& S, const Epi& E) {
;     ...
;             PG8_WAIT_V(8); PG8_WAIT_L(0); PG8_BAR; PG8_MMA(0, 0, At, B0); PG8_MMA(0, 1, At, B1); PG8_BAR; PG8_SCHED;
;             PG8_LDA(At, 1, 1); PG8_STAGE(PG8_SB(1, 0), b3, voffB); PG8_STAGE(PG8_SB(1, 1), b3 + hstep, voffB); PG8_STAGE(PG8_SA(1, 0), a3, voffA);
;             PG8_WAIT_V(8); PG8_WAIT_L(0); PG8_BAR; PG8_MMA(1, 0, At, B0); PG8_MMA(1, 1, At, B1); PG8_BAR; PG8_SCHED;
;     ...
;         if constexpr (ALIGN_EPI) { if (wr == 0) PG8_BAR; }
;         if constexpr (!Epi::AFTER_DRAIN) { E(acc, cur, wr, wc, fr, fq); S.done(cur); }
;         if (!has_next) break;
	s_setprio 1
	s_waitcnt lgkmcnt(0)
	v_mfma_f32_16x16x32_bf16 v[126:129], v[130:133], v[182:185], v[126:129]
	v_mfma_f32_16x16x32_bf16 v[122:125], v[138:141], v[182:185], v[122:125]
	v_mfma_f32_16x16x32_bf16 v[118:121], v[130:133], v[190:193], v[118:121]
	v_mfma_f32_16x16x32_bf16 v[110:113], v[138:141], v[190:193], v[110:113]
	v_mfma_f32_16x16x32_bf16 v[102:105], v[130:133], v[198:201], v[102:105]
	v_mfma_f32_16x16x32_bf16 v[94:97], v[138:141], v[198:201], v[94:97]
	v_mfma_f32_16x16x32_bf16 v[86:89], v[130:133], v[206:209], v[86:89]
	v_mfma_f32_16x16x32_bf16 v[78:81], v[138:141], v[206:209], v[78:81]
	v_mfma_f32_16x16x32_bf16 v[126:129], v[134:137], v[186:189], v[126:129]
	v_mfma_f32_16x16x32_bf16 v[122:125], v[142:145], v[186:189], v[122:125]
	v_mfma_f32_16x16x32_bf16 v[118:121], v[134:137], v[194:197], v[118:121]
	v_mfma_f32_16x16x32_bf16 v[110:113], v[142:145], v[194:197], v[110:113]
	v_mfma_f32_16x16x32_bf16 v[102:105], v[134:137], v[202:205], v[102:105]
	v_mfma_f32_16x16x32_bf16 v[94:97], v[142:145], v[202:205], v[94:97]
	v_mfma_f32_16x16x32_bf16 v[86:89], v[134:137], v[224:227], v[86:89]
	v_mfma_f32_16x16x32_bf16 v[78:81], v[142:145], v[224:227], v[78:81]
	s_setprio 0
	s_setprio 1
	v_mfma_f32_16x16x32_bf16 v[114:117], v[152:155], v[182:185], v[114:117]
	v_mfma_f32_16x16x32_bf16 v[106:109], v[166:169], v[182:185], v[106:109]
	v_mfma_f32_16x16x32_bf16 v[98:101], v[152:155], v[190:193], v[98:101]
	v_mfma_f32_16x16x32_bf16 v[90:93], v[166:169], v[190:193], v[90:93]
	v_mfma_f32_16x16x32_bf16 v[82:85], v[152:155], v[198:201], v[82:85]
	v_mfma_f32_16x16x32_bf16 v[74:77], v[166:169], v[198:201], v[74:77]
	v_mfma_f32_16x16x32_bf16 v[70:73], v[152:155], v[206:209], v[70:73]
	v_mfma_f32_16x16x32_bf16 v[66:69], v[166:169], v[206:209], v[66:69]
	v_mfma_f32_16x16x32_bf16 v[114:117], v[162:165], v[186:189], v[114:117]
	v_mfma_f32_16x16x32_bf16 v[106:109], v[178:181], v[186:189], v[106:109]
	v_mfma_f32_16x16x32_bf16 v[98:101], v[162:165], v[194:197], v[98:101]
	v_mfma_f32_16x16x32_bf16 v[90:93], v[178:181], v[194:197], v[90:93]
	v_mfma_f32_16x16x32_bf16 v[82:85], v[162:165], v[202:205], v[82:85]
	v_mfma_f32_16x16x32_bf16 v[74:77], v[178:181], v[202:205], v[74:77]
	v_mfma_f32_16x16x32_bf16 v[70:73], v[162:165], v[224:227], v[70:73]
	v_mfma_f32_16x16x32_bf16 v[66:69], v[178:181], v[224:227], v[66:69]
	s_setprio 0
	s_barrier
	s_add_i32 s24, s57, s43
	v_lshl_add_u64 v[156:157], v[156:157], 0, s[88:89]
	s_mov_b32 m0, s24
	ds_read_b128 v[182:185], v161 offset:49152
	ds_read_b128 v[186:189], v161 offset:50176
	ds_read_b128 v[190:193], v161 offset:51200
	ds_read_b128 v[194:197], v161 offset:52224
	ds_read_b128 v[198:201], v161 offset:53248
	ds_read_b128 v[202:205], v161 offset:54272
	ds_read_b128 v[206:209], v161 offset:55296
	ds_read_b128 v[224:227], v161 offset:56320
	global_load_lds_dwordx4 v[156:157], off
	s_add_i32 m0, s24, 0x2000
	s_add_u32 s24, s30, 0x40080
	v_lshl_add_u64 v[156:157], v[210:211], 0, s[88:89]
	s_addc_u32 s25, s31, 0
	s_add_i32 s30, s58, s43
	global_load_lds_dwordx4 v[156:157], off
	v_lshl_add_u64 v[156:157], s[24:25], 0, v[0:1]
	s_mov_b32 m0, s30
	s_nop 0
	global_load_lds_dwordx4 v[156:157], off
	v_lshl_add_u64 v[156:157], s[24:25], 0, v[146:147]
	s_add_i32 m0, s30, 0x2000
	s_nop 0
	global_load_lds_dwordx4 v[156:157], off
	v_lshl_add_u64 v[156:157], v[228:229], 0, s[88:89]
	s_mov_b32 m0, s73
	s_nop 0
	global_load_lds_dwordx4 v[156:157], off
	v_lshl_add_u64 v[156:157], v[230:231], 0, s[88:89]
	s_mov_b32 m0, s74
	s_nop 0
	global_load_lds_dwordx4 v[156:157], off
	s_waitcnt vmcnt(8)
	s_waitcnt lgkmcnt(0)
	s_barrier
	s_setprio 1
	s_waitcnt lgkmcnt(0)
	v_mfma_f32_16x16x32_bf16 v[62:65], v[130:133], v[182:185], v[62:65]
	v_mfma_f32_16x16x32_bf16 v[58:61], v[138:141], v[182:185], v[58:61]
	v_mfma_f32_16x16x32_bf16 v[54:57], v[130:133], v[190:193], v[54:57]
	v_mfma_f32_16x16x32_bf16 v[46:49], v[138:141], v[190:193], v[46:49]
	v_mfma_f32_16x16x32_bf16 v[38:41], v[130:133], v[198:201], v[38:41]
	v_mfma_f32_16x16x32_bf16 v[30:33], v[138:141], v[198:201], v[30:33]
	v_mfma_f32_16x16x32_bf16 v[22:25], v[130:133], v[206:209], v[22:25]
	v_mfma_f32_16x16x32_bf16 v[14:17], v[138:141], v[206:209], v[14:17]
	v_mfma_f32_16x16x32_bf16 v[62:65], v[134:137], v[186:189], v[62:65]
	v_mfma_f32_16x16x32_bf16 v[58:61], v[142:145], v[186:189], v[58:61]
	v_mfma_f32_16x16x32_bf16 v[54:57], v[134:137], v[194:197], v[54:57]
	v_mfma_f32_16x16x32_bf16 v[46:49], v[142:145], v[194:197], v[46:49]
	v_mfma_f32_16x16x32_bf16 v[38:41], v[134:137], v[202:205], v[38:41]
	v_mfma_f32_16x16x32_bf16 v[30:33], v[142:145], v[202:205], v[30:33]
	v_mfma_f32_16x16x32_bf16 v[22:25], v[134:137], v[224:227], v[22:25]
	v_mfma_f32_16x16x32_bf16 v[14:17], v[142:145], v[224:227], v[14:17]
	s_setprio 0
	s_setprio 1
	v_mfma_f32_16x16x32_bf16 v[50:53], v[152:155], v[182:185], v[50:53]
	v_mfma_f32_16x16x32_bf16 v[42:45], v[166:169], v[182:185], v[42:45]
	v_mfma_f32_16x16x32_bf16 v[34:37], v[152:155], v[190:193], v[34:37]
	v_mfma_f32_16x16x32_bf16 v[26:29], v[166:169], v[190:193], v[26:29]
	v_mfma_f32_16x16x32_bf16 v[18:21], v[152:155], v[198:201], v[18:21]
	v_mfma_f32_16x16x32_bf16 v[10:13], v[166:169], v[198:201], v[10:13]
	v_mfma_f32_16x16x32_bf16 v[6:9], v[152:155], v[206:209], v[6:9]
	v_mfma_f32_16x16x32_bf16 v[2:5], v[166:169], v[206:209], v[2:5]
	v_mfma_f32_16x16x32_bf16 v[50:53], v[162:165], v[186:189], v[50:53]
	v_mfma_f32_16x16x32_bf16 v[42:45], v[178:181], v[186:189], v[42:45]
	v_mfma_f32_16x16x32_bf16 v[34:37], v[162:165], v[194:197], v[34:37]
	v_mfma_f32_16x16x32_bf16 v[26:29], v[178:181], v[194:197], v[26:29]
	v_mfma_f32_16x16x32_bf16 v[18:21], v[162:165], v[202:205], v[18:21]
	v_mfma_f32_16x16x32_bf16 v[10:13], v[178:181], v[202:205], v[10:13]
	v_mfma_f32_16x16x32_bf16 v[6:9], v[162:165], v[224:227], v[6:9]
	v_mfma_f32_16x16x32_bf16 v[2:5], v[178:181], v[224:227], v[2:5]
	s_setprio 0
	s_barrier
	s_add_i32 s56, s56, 2
	s_add_u32 s52, s52, 0x100
	s_addc_u32 s54, s54, 0
	s_cmp_gt_u32 s56, 13
	s_mov_b64 s[24:25], s[28:29]
	s_cbranch_scc0 .LBB0_153
	s_and_b64 vcc, exec, s[8:9]
	s_cbranch_vccz .LBB0_156
	s_barrier

; #define PG8_STAGE(bufoff, gbase, voff) do { _Pragma("unroll") for (int _i = 0; _i < 2; ++_i) \
;         __builtin_amdgcn_global_load_lds((const unsigned*)((const char*)(gbase) + (voff)[_i]), (PG8_LAS unsigned*)(lds + (bufoff) + ldsw + _i * 8192), 16, 0, 0); } while (0)
; #define PG8_LDA(dst, b, h) do { _Pragma("unroll") for (int m = 0; m < 4; ++m) _Pragma("unroll") for (int k = 0; k < 2; ++k) dst[m][k] = *(const PG8_LAS bf16x8*)(lds + PG8_SA(b, h) + aoff + m * 2048 + k * 1024); } while (0)
; #define PG8_LDB(dst, b, h) do { _Pragma("unroll") for (int n = 0; n < 2; ++n) _Pragma("unroll") for (int k = 0; k < 2; ++k) dst[n][k] = *(const PG8_LAS bf16x8*)(lds + PG8_SB(b, h) + boff + n * 2048 + k * 1024); } while (0)
; #define PG8_WAIT_V(n) asm volatile("s_waitcnt vmcnt(" #n ")" ::: "memory")
; #define PG8_WAIT_L(n) asm volatile("s_waitcnt lgkmcnt(" #n ")" ::: "memory")
; #define PG8_BAR __builtin_amdgcn_s_barrier()
; #define PG8_SCHED __builtin_amdgcn_sched_barrier(0)
; template <class Epi, class Sched, bool ALIGN_EPI = false, bool SP2 = false>
; __device__ __forceinline__ void gemm_phase(PG8_LAS unsigned char* lds, const Gemm g, const Sched& S, const Epi& E) {
;     ...
;         const char* nA = has_next ? (const char*)g.A + (size_t)nxt.pm * tstep : cA; const char* nB = has_next ? (const char*)g.Bt + (size_t)nxt.pn * tstep : cB;
;         for (int t = 0; t < nt; t += 2) {
;             const bool last = (t == nt - 2);
;             const char* a1 = cA + (size_t)(t + 1) * kstep;
;             const char* a2 = last ? nA : cA + (size_t)(t + 2) * kstep; const char* b2 = last ? nB : cB + (size_t)(t + 2) * kstep;
;             const char* a3 = a2 + kstep; const char* b3 = b2 + kstep;
;             if (last && has_next) S.a_ready(nxt);
;             if constexpr (SP2) {
;             PG8_LDB(B0, 0, 0); PG8_LDB(B1, 0, 1); PG8_SCHED; PG8_LDA(At, 0, 0); PG8_STAGE(PG8_SA(1, 1), a1 + hstep, voffA);
;             PG8_WAIT_V(8); PG8_WAIT_L(0); PG8_BAR; PG8_MMA(0, 0, At, B0); PG8_MMA(0, 1, At, B1); PG8_BAR; PG8_SCHED;
;     ...
; #pragma unroll
;         for (int a = 0; a < 2; ++a)
; #pragma unroll
;             for (int b = 0; b < 2; ++b)
; #pragma unroll
;                 for (int m = 0; m < 4; ++m)
; #pragma unroll
;                     for (int n = 0; n < 2; ++n) acc[a][b][m][n] = (f32x4){0.f, 0.f, 0.f, 0.f};
.LBB0_676:
	s_ashr_i32 s15, s14, 31
	s_lshl_b64 s[16:17], s[14:15], 19
	s_add_u32 s16, s26, s16
	s_addc_u32 s17, s27, s17
	s_and_b64 s[18:19], s[6:7], exec
	s_cselect_b32 s15, s17, s25
	s_cselect_b32 s72, s16, s24
	s_ashr_i32 s13, s12, 31
	s_lshl_b64 s[18:19], s[12:13], 19
	s_add_u32 s18, s34, s18
	s_addc_u32 s19, s35, s19
	s_and_b64 s[28:29], s[6:7], exec
	s_cselect_b32 s13, s19, s23
	s_cselect_b32 s45, s18, s22
	s_add_u32 s73, s22, 0x100
	s_addc_u32 s52, s23, 0
	s_add_u32 s22, s24, 0x40080
	s_addc_u32 s23, s25, 0
	s_mov_b32 s54, -2
	v_mov_b64_e32 v[2:3], 0
	v_mov_b64_e32 v[4:5], 0
	v_mov_b64_e32 v[6:7], 0
	v_mov_b64_e32 v[8:9], 0
	v_mov_b64_e32 v[10:11], 0
	v_mov_b64_e32 v[12:13], 0
	v_mov_b64_e32 v[14:15], 0
	v_mov_b64_e32 v[16:17], 0
	v_mov_b64_e32 v[18:19], 0
	v_mov_b64_e32 v[20:21], 0
	v_mov_b64_e32 v[22:23], 0
	v_mov_b64_e32 v[24:25], 0
	v_mov_b64_e32 v[26:27], 0
	v_mov_b64_e32 v[28:29], 0
	v_mov_b64_e32 v[30:31], 0
	v_mov_b64_e32 v[32:33], 0
	v_mov_b64_e32 v[34:35], 0
	v_mov_b64_e32 v[36:37], 0
	v_mov_b64_e32 v[38:39], 0
	v_mov_b64_e32 v[40:41], 0
	v_mov_b64_e32 v[42:43], 0
	v_mov_b64_e32 v[44:45], 0
	v_mov_b64_e32 v[46:47], 0
	v_mov_b64_e32 v[48:49], 0
	v_mov_b64_e32 v[50:51], 0
	v_mov_b64_e32 v[52:53], 0
	v_mov_b64_e32 v[54:55], 0
	v_mov_b64_e32 v[56:57], 0
	v_mov_b64_e32 v[58:59], 0
	v_mov_b64_e32 v[60:61], 0
	v_mov_b64_e32 v[62:63], 0
	v_mov_b64_e32 v[64:65], 0
	v_mov_b64_e32 v[66:67], 0
	v_mov_b64_e32 v[68:69], 0
	v_mov_b64_e32 v[70:71], 0
	v_mov_b64_e32 v[72:73], 0
	v_mov_b64_e32 v[74:75], 0
	v_mov_b64_e32 v[76:77], 0
	v_mov_b64_e32 v[78:79], 0
	v_mov_b64_e32 v[80:81], 0
	v_mov_b64_e32 v[82:83], 0
	v_mov_b64_e32 v[84:85], 0
	v_mov_b64_e32 v[86:87], 0
	v_mov_b64_e32 v[88:89], 0
	v_mov_b64_e32 v[90:91], 0
	v_mov_b64_e32 v[92:93], 0
	v_mov_b64_e32 v[94:95], 0
	v_mov_b64_e32 v[96:97], 0
	v_mov_b64_e32 v[98:99], 0
	v_mov_b64_e32 v[100:101], 0
	v_mov_b64_e32 v[102:103], 0
	v_mov_b64_e32 v[104:105], 0
	v_mov_b64_e32 v[106:107], 0
	v_mov_b64_e32 v[108:109], 0
	v_mov_b64_e32 v[110:111], 0
	v_mov_b64_e32 v[112:113], 0
	v_mov_b64_e32 v[114:115], 0
	v_mov_b64_e32 v[116:117], 0
	v_mov_b64_e32 v[118:119], 0
	v_mov_b64_e32 v[120:121], 0
	v_mov_b64_e32 v[122:123], 0
	v_mov_b64_e32 v[124:125], 0
	v_mov_b64_e32 v[126:127], 0
	v_mov_b64_e32 v[128:129], 0
	s_branch .Lz64_3
	s_nop 0
	s_nop 0
	s_nop 0
	s_nop 0
	s_nop 0
	s_nop 0
	s_nop 0
	s_nop 0
	s_nop 0
	s_nop 0
	s_nop 0
	s_nop 0
	s_nop 0
	s_nop 0
	s_nop 0
	s_nop 0
	s_nop 0
	s_nop 0
	s_nop 0
	s_nop 0
	s_nop 0
	s_nop 0
	s_nop 0
	s_nop 0
	s_nop 0
	s_nop 0
	s_nop 0
	s_nop 0
	s_nop 0
	s_nop 0
	s_nop 0
	s_nop 0
	s_nop 0
	s_nop 0
	s_nop 0
	s_nop 0
	s_nop 0
	s_nop 0
	s_nop 0
	s_nop 0
	s_nop 0
	s_nop 0
	s_nop 0
	s_nop 0
	s_nop 0
	s_nop 0
	s_nop 0
	s_nop 0
	s_nop 0
	s_nop 0
	s_nop 0
	s_nop 0
	s_nop 0
	s_nop 0
	s_nop 0
	s_nop 0
	s_nop 0
	s_nop 0
	s_nop 0
	s_nop 0
	s_nop 0
	s_nop 0
	s_nop 0
.Lz64_3:
.LBB0_677:
	s_add_u32 s24, s22, 0xfffc0080
	s_addc_u32 s25, s23, -1
	s_add_i32 s56, 0, 0x10000
	s_cmp_eq_u32 s54, 12
	s_cselect_b32 s29, s15, s25
	s_cselect_b32 s28, s72, s24
	v_add_u32_e32 v140, s56, v143
	s_cselect_b32 s25, s13, s52
	s_cselect_b32 s24, s45, s73
	s_add_i32 s58, 0, 0x14000
	ds_read_b128 v[146:149], v140
	ds_read_b128 v[150:153], v140 offset:1024
	ds_read_b128 v[154:157], v140 offset:2048
	ds_read_b128 v[158:161], v140 offset:3072
	v_add_u32_e32 v140, s58, v143
	ds_read_b128 v[162:165], v140
	ds_read_b128 v[166:169], v140 offset:1024
	ds_read_b128 v[178:181], v140 offset:2048
	ds_read_b128 v[182:185], v140 offset:3072
	v_lshl_add_u64 v[140:141], s[22:23], 0, v[138:139]
	s_add_i32 m0, s21, 0xc000
	ds_read_b128 v[186:189], v145
	ds_read_b128 v[190:193], v145 offset:1024
	ds_read_b128 v[194:197], v145 offset:2048
	ds_read_b128 v[198:201], v145 offset:3072
	ds_read_b128 v[202:205], v145 offset:4096
	ds_read_b128 v[206:209], v145 offset:5120
	ds_read_b128 v[224:227], v145 offset:6144
	ds_read_b128 v[228:231], v145 offset:7168
	global_load_lds_dwordx4 v[140:141], off
	v_lshl_add_u64 v[140:141], s[22:23], 0, v[136:137]
	s_add_i32 m0, s21, 0xe000
	s_nop 0
	global_load_lds_dwordx4 v[140:141], off
	s_waitcnt vmcnt(8)
	s_waitcnt lgkmcnt(0)
	s_barrier
	s_setprio 1
	s_waitcnt lgkmcnt(0)
	v_mfma_f32_16x16x32_bf16 v[126:129], v[146:149], v[186:189], v[126:129]
	v_mfma_f32_16x16x32_bf16 v[122:125], v[154:157], v[186:189], v[122:125]
	v_mfma_f32_16x16x32_bf16 v[118:121], v[146:149], v[194:197], v[118:121]
	v_mfma_f32_16x16x32_bf16 v[110:113], v[154:157], v[194:197], v[110:113]
	v_mfma_f32_16x16x32_bf16 v[102:105], v[146:149], v[202:205], v[102:105]
	v_mfma_f32_16x16x32_bf16 v[94:97], v[154:157], v[202:205], v[94:97]
	v_mfma_f32_16x16x32_bf16 v[86:89], v[146:149], v[224:227], v[86:89]
	v_mfma_f32_16x16x32_bf16 v[78:81], v[154:157], v[224:227], v[78:81]
	v_mfma_f32_16x16x32_bf16 v[126:129], v[150:153], v[190:193], v[126:129]
	v_mfma_f32_16x16x32_bf16 v[122:125], v[158:161], v[190:193], v[122:125]
	v_mfma_f32_16x16x32_bf16 v[118:121], v[150:153], v[198:201], v[118:121]
	v_mfma_f32_16x16x32_bf16 v[110:113], v[158:161], v[198:201], v[110:113]
	v_mfma_f32_16x16x32_bf16 v[102:105], v[150:153], v[206:209], v[102:105]
	v_mfma_f32_16x16x32_bf16 v[94:97], v[158:161], v[206:209], v[94:97]
	v_mfma_f32_16x16x32_bf16 v[86:89], v[150:153], v[228:231], v[86:89]
	v_mfma_f32_16x16x32_bf16 v[78:81], v[158:161], v[228:231], v[78:81]
	s_setprio 0
	s_setprio 1
	v_mfma_f32_16x16x32_bf16 v[114:117], v[162:165], v[186:189], v[114:117]
	v_mfma_f32_16x16x32_bf16 v[106:109], v[178:181], v[186:189], v[106:109]
	v_mfma_f32_16x16x32_bf16 v[98:101], v[162:165], v[194:197], v[98:101]
	v_mfma_f32_16x16x32_bf16 v[90:93], v[178:181], v[194:197], v[90:93]
	v_mfma_f32_16x16x32_bf16 v[82:85], v[162:165], v[202:205], v[82:85]
	v_mfma_f32_16x16x32_bf16 v[74:77], v[178:181], v[202:205], v[74:77]
	v_mfma_f32_16x16x32_bf16 v[70:73], v[162:165], v[224:227], v[70:73]
	v_mfma_f32_16x16x32_bf16 v[66:69], v[178:181], v[224:227], v[66:69]
	v_mfma_f32_16x16x32_bf16 v[114:117], v[166:169], v[190:193], v[114:117]
	v_mfma_f32_16x16x32_bf16 v[106:109], v[182:185], v[190:193], v[106:109]
	v_mfma_f32_16x16x32_bf16 v[98:101], v[166:169], v[198:201], v[98:101]
	v_mfma_f32_16x16x32_bf16 v[90:93], v[182:185], v[198:201], v[90:93]
	v_mfma_f32_16x16x32_bf16 v[82:85], v[166:169], v[206:209], v[82:85]
	v_mfma_f32_16x16x32_bf16 v[74:77], v[182:185], v[206:209], v[74:77]
	v_mfma_f32_16x16x32_bf16 v[70:73], v[166:169], v[228:231], v[70:73]
	v_mfma_f32_16x16x32_bf16 v[66:69], v[182:185], v[228:231], v[66:69]
	s_setprio 0
	s_barrier
; #define PG8_STAGE(bufoff, gbase, voff) do { _Pragma("unroll") for (int _i = 0; _i < 2; ++_i) \
;         __builtin_amdgcn_global_load_lds((const unsigned*)((const char*)(gbase) + (voff)[_i]), (PG8_LAS unsigned*)(lds + (bufoff) + ldsw + _i * 8192), 16, 0, 0); } while (0)
; #define PG8_LDA(dst, b, h) do { _Pragma("unroll") for (int m = 0; m < 4; ++m) _Pragma("unroll") for (int k = 0; k < 2; ++k) dst[m][k] = *(const PG8_LAS bf16x8*)(lds + PG8_SA(b, h) + aoff + m * 2048 + k * 1024); } while (0)
; #define PG8_LDB(dst, b, h) do { _Pragma("unroll") for (int n = 0; n < 2; ++n) _Pragma("unroll") for (int k = 0; k < 2; ++k) dst[n][k] = *(const PG8_LAS bf16x8*)(lds + PG8_SB(b, h) + boff + n * 2048 + k * 1024); } while (0)
; #define PG8_MMA(ai, bj, At, Bt) do { __builtin_amdgcn_s_setprio(1); _Pragma("unroll") for (int m = 0; m < 4; ++m) _Pragma("unroll") for (int n = 0; n < 2; ++n) _Pragma("unroll") for (int k = 0; k < 2; ++k) \
;         acc[ai][bj][m][n] = __builtin_amdgcn_mfma_f32_16x16x32_bf16(Bt[n][k], At[m][k], acc[ai][bj][m][n], 0, 0, 0); __builtin_amdgcn_s_setprio(0); } while (0)
; #define PG8_WAIT_V(n) asm volatile("s_waitcnt vmcnt(" #n ")" ::: "memory")
; #define PG8_WAIT_L(n) asm volatile("s_waitcnt lgkmcnt(" #n ")" ::: "memory")
; #define PG8_BAR __builtin_amdgcn_s_barrier()
; #define PG8_SCHED __builtin_amdgcn_sched_barrier(0)
; template <class Epi, class Sched, bool ALIGN_EPI = false, bool SP2 = false>
; __device__ __forceinline__ void gemm_phase(PG8_LAS unsigned char* lds, const Gemm g, const Sched& S, const Epi& E) {
;     ...
;             PG8_LDA(At, 0, 1); PG8_STAGE(PG8_SB(0, 0), b2, voffB); PG8_STAGE(PG8_SB(0, 1), b2 + hstep, voffB); PG8_STAGE(PG8_SA(0, 0), a2, voffA);
;             PG8_WAIT_V(8); PG8_WAIT_L(0); PG8_BAR; PG8_MMA(1, 0, At, B0); PG8_MMA(1, 1, At, B1); PG8_BAR; PG8_SCHED;
;             PG8_LDB(B0, 1, 0); PG8_LDB(B1, 1, 1); PG8_SCHED; PG8_LDA(At, 1, 0); PG8_STAGE(PG8_SA(0, 1), a2 + hstep, voffA);
	s_add_i32 s56, s56, s36
	v_lshl_add_u64 v[140:141], s[24:25], 0, v[0:1]
	s_mov_b32 m0, s56
	ds_read_b128 v[186:189], v145 offset:16384
	ds_read_b128 v[190:193], v145 offset:17408
	ds_read_b128 v[194:197], v145 offset:18432
	ds_read_b128 v[198:201], v145 offset:19456
	ds_read_b128 v[202:205], v145 offset:20480
	ds_read_b128 v[206:209], v145 offset:21504
	ds_read_b128 v[224:227], v145 offset:22528
	ds_read_b128 v[228:231], v145 offset:23552
	global_load_lds_dwordx4 v[140:141], off
	s_add_i32 m0, s56, 0x2000
	s_add_u32 s56, s24, 0x40000
	v_lshl_add_u64 v[210:211], s[24:25], 0, v[130:131]
	s_addc_u32 s57, s25, 0
	s_add_i32 s58, s58, s36
	global_load_lds_dwordx4 v[210:211], off
	v_lshl_add_u64 v[232:233], s[56:57], 0, v[0:1]
	s_mov_b32 m0, s58
	v_lshl_add_u64 v[234:235], s[28:29], 0, v[132:133]
	global_load_lds_dwordx4 v[232:233], off
	v_lshl_add_u64 v[232:233], s[56:57], 0, v[130:131]
	s_add_i32 m0, s58, 0x2000
	s_nop 0
	global_load_lds_dwordx4 v[232:233], off
	v_lshl_add_u64 v[232:233], s[28:29], 0, v[134:135]
	s_mov_b32 m0, s21
	s_nop 0
	global_load_lds_dwordx4 v[232:233], off
	s_mov_b32 m0, s38
	s_nop 0
	global_load_lds_dwordx4 v[234:235], off
	s_waitcnt vmcnt(8)
	s_waitcnt lgkmcnt(0)
	s_barrier
	s_setprio 1
	s_waitcnt lgkmcnt(0)
	v_mfma_f32_16x16x32_bf16 v[62:65], v[146:149], v[186:189], v[62:65]
	v_mfma_f32_16x16x32_bf16 v[58:61], v[154:157], v[186:189], v[58:61]
	v_mfma_f32_16x16x32_bf16 v[50:53], v[146:149], v[194:197], v[50:53]
	v_mfma_f32_16x16x32_bf16 v[42:45], v[154:157], v[194:197], v[42:45]
	v_mfma_f32_16x16x32_bf16 v[34:37], v[146:149], v[202:205], v[34:37]
	v_mfma_f32_16x16x32_bf16 v[26:29], v[154:157], v[202:205], v[26:29]
	v_mfma_f32_16x16x32_bf16 v[18:21], v[146:149], v[224:227], v[18:21]
	v_mfma_f32_16x16x32_bf16 v[10:13], v[154:157], v[224:227], v[10:13]
	v_mfma_f32_16x16x32_bf16 v[62:65], v[150:153], v[190:193], v[62:65]
	v_mfma_f32_16x16x32_bf16 v[58:61], v[158:161], v[190:193], v[58:61]
	v_mfma_f32_16x16x32_bf16 v[50:53], v[150:153], v[198:201], v[50:53]
	v_mfma_f32_16x16x32_bf16 v[42:45], v[158:161], v[198:201], v[42:45]
	v_mfma_f32_16x16x32_bf16 v[34:37], v[150:153], v[206:209], v[34:37]
	v_mfma_f32_16x16x32_bf16 v[26:29], v[158:161], v[206:209], v[26:29]
	v_mfma_f32_16x16x32_bf16 v[18:21], v[150:153], v[228:231], v[18:21]
	v_mfma_f32_16x16x32_bf16 v[10:13], v[158:161], v[228:231], v[10:13]
	s_setprio 0
	s_setprio 1
	v_mfma_f32_16x16x32_bf16 v[54:57], v[162:165], v[186:189], v[54:57]
	v_mfma_f32_16x16x32_bf16 v[46:49], v[178:181], v[186:189], v[46:49]
	v_mfma_f32_16x16x32_bf16 v[38:41], v[162:165], v[194:197], v[38:41]
	v_mfma_f32_16x16x32_bf16 v[30:33], v[178:181], v[194:197], v[30:33]
	v_mfma_f32_16x16x32_bf16 v[22:25], v[162:165], v[202:205], v[22:25]
	v_mfma_f32_16x16x32_bf16 v[14:17], v[178:181], v[202:205], v[14:17]
	v_mfma_f32_16x16x32_bf16 v[6:9], v[162:165], v[224:227], v[6:9]
	v_mfma_f32_16x16x32_bf16 v[2:5], v[178:181], v[224:227], v[2:5]
	v_mfma_f32_16x16x32_bf16 v[54:57], v[166:169], v[190:193], v[54:57]
	v_mfma_f32_16x16x32_bf16 v[46:49], v[182:185], v[190:193], v[46:49]
	v_mfma_f32_16x16x32_bf16 v[38:41], v[166:169], v[198:201], v[38:41]
	v_mfma_f32_16x16x32_bf16 v[30:33], v[182:185], v[198:201], v[30:33]
	v_mfma_f32_16x16x32_bf16 v[22:25], v[166:169], v[206:209], v[22:25]
	v_mfma_f32_16x16x32_bf16 v[14:17], v[182:185], v[206:209], v[14:17]
	v_mfma_f32_16x16x32_bf16 v[6:9], v[166:169], v[228:231], v[6:9]
	v_mfma_f32_16x16x32_bf16 v[2:5], v[182:185], v[228:231], v[2:5]
	s_setprio 0
	s_barrier
	s_add_i32 s56, 0, 0x18000
	s_add_i32 s57, 0, 0x1c000
	v_add_u32_e32 v158, s56, v143
	v_add_u32_e32 v182, s57, v143
	ds_read_b128 v[146:149], v158
	ds_read_b128 v[150:153], v158 offset:1024
	ds_read_b128 v[154:157], v158 offset:2048
	ds_read_b128 v[158:161], v158 offset:3072
	ds_read_b128 v[162:165], v182
	ds_read_b128 v[166:169], v182 offset:1024
	ds_read_b128 v[178:181], v182 offset:2048
	ds_read_b128 v[182:185], v182 offset:3072
	s_add_u32 s28, s28, 0x40000
	s_addc_u32 s29, s29, 0
	s_mov_b32 m0, s39
	v_lshl_add_u64 v[236:237], s[28:29], 0, v[134:135]
	ds_read_b128 v[186:189], v145 offset:32768
	ds_read_b128 v[190:193], v145 offset:33792
	ds_read_b128 v[194:197], v145 offset:34816
	ds_read_b128 v[198:201], v145 offset:35840
	ds_read_b128 v[202:205], v145 offset:36864
	ds_read_b128 v[206:209], v145 offset:37888
	ds_read_b128 v[224:227], v145 offset:38912
	ds_read_b128 v[228:231], v145 offset:39936
	global_load_lds_dwordx4 v[236:237], off
	v_lshl_add_u64 v[236:237], s[28:29], 0, v[132:133]
	s_mov_b32 m0, s41
	s_nop 0
	global_load_lds_dwordx4 v[236:237], off
	s_waitcnt vmcnt(8)
	s_waitcnt lgkmcnt(0)
	s_barrier
; #define PG8_STAGE(bufoff, gbase, voff) do { _Pragma("unroll") for (int _i = 0; _i < 2; ++_i) \
;         __builtin_amdgcn_global_load_lds((const unsigned*)((const char*)(gbase) + (voff)[_i]), (PG8_LAS unsigned*)(lds + (bufoff) + ldsw + _i * 8192), 16, 0, 0); } while (0)
; #define PG8_LDA(dst, b, h) do { _Pragma("unroll") for (int m = 0; m < 4; ++m) _Pragma("unroll") for (int k = 0; k < 2; ++k) dst[m][k] = *(const PG8_LAS bf16x8*)(lds + PG8_SA(b, h) + aoff + m * 2048 + k * 1024); } while (0)
; #define PG8_MMA(ai, bj, At, Bt) do { __builtin_amdgcn_s_setprio(1); _Pragma("unroll") for (int m = 0; m < 4; ++m) _Pragma("unroll") for (int n = 0; n < 2; ++n) _Pragma("unroll") for (int k = 0; k < 2; ++k) \
;         acc[ai][bj][m][n] = __builtin_amdgcn_mfma_f32_16x16x32_bf16(Bt[n][k], At[m][k], acc[ai][bj][m][n], 0, 0, 0); __builtin_amdgcn_s_setprio(0); } while (0)
; #define PG8_WAIT_V(n) asm volatile("s_waitcnt vmcnt(" #n ")" ::: "memory")
; #define PG8_WAIT_L(n) asm volatile("s_waitcnt lgkmcnt(" #n ")" ::: "memory")
; #define PG8_BAR __builtin_amdgcn_s_barrier()
; #define PG8_SCHED __builtin_amdgcn_sched_barrier(0)
; template <class Epi, class Sched, bool ALIGN_EPI = false, bool SP2 = false>
; __device__ __forceinline__ void gemm_phase(PG8_LAS unsigned char* lds, const Gemm g, const Sched& S, const Epi& E) {
;     ...
;             PG8_WAIT_V(8); PG8_WAIT_L(0); PG8_BAR; PG8_MMA(0, 0, At, B0); PG8_MMA(0, 1, At, B1); PG8_BAR; PG8_SCHED;
;             PG8_LDA(At, 1, 1); PG8_STAGE(PG8_SB(1, 0), b3, voffB); PG8_STAGE(PG8_SB(1, 1), b3 + hstep, voffB); PG8_STAGE(PG8_SA(1, 0), a3, voffA);
;             PG8_WAIT_V(8); PG8_WAIT_L(0); PG8_BAR; PG8_MMA(1, 0, At, B0); PG8_MMA(1, 1, At, B1); PG8_BAR; PG8_SCHED;
;     ...
;         if constexpr (ALIGN_EPI) { if (wr == 0) PG8_BAR; }
;         if constexpr (!Epi::AFTER_DRAIN) { E(acc, cur, wr, wc, fr, fq); S.done(cur); }
;         if (!has_next) break;
	s_setprio 1
	s_waitcnt lgkmcnt(0)
	v_mfma_f32_16x16x32_bf16 v[126:129], v[146:149], v[186:189], v[126:129]
	v_mfma_f32_16x16x32_bf16 v[122:125], v[154:157], v[186:189], v[122:125]
	v_mfma_f32_16x16x32_bf16 v[118:121], v[146:149], v[194:197], v[118:121]
	v_mfma_f32_16x16x32_bf16 v[110:113], v[154:157], v[194:197], v[110:113]
	v_mfma_f32_16x16x32_bf16 v[102:105], v[146:149], v[202:205], v[102:105]
	v_mfma_f32_16x16x32_bf16 v[94:97], v[154:157], v[202:205], v[94:97]
	v_mfma_f32_16x16x32_bf16 v[86:89], v[146:149], v[224:227], v[86:89]
	v_mfma_f32_16x16x32_bf16 v[78:81], v[154:157], v[224:227], v[78:81]
	v_mfma_f32_16x16x32_bf16 v[126:129], v[150:153], v[190:193], v[126:129]
	v_mfma_f32_16x16x32_bf16 v[122:125], v[158:161], v[190:193], v[122:125]
	v_mfma_f32_16x16x32_bf16 v[118:121], v[150:153], v[198:201], v[118:121]
	v_mfma_f32_16x16x32_bf16 v[110:113], v[158:161], v[198:201], v[110:113]
	v_mfma_f32_16x16x32_bf16 v[102:105], v[150:153], v[206:209], v[102:105]
	v_mfma_f32_16x16x32_bf16 v[94:97], v[158:161], v[206:209], v[94:97]
	v_mfma_f32_16x16x32_bf16 v[86:89], v[150:153], v[228:231], v[86:89]
	v_mfma_f32_16x16x32_bf16 v[78:81], v[158:161], v[228:231], v[78:81]
	s_setprio 0
	s_setprio 1
	v_mfma_f32_16x16x32_bf16 v[114:117], v[162:165], v[186:189], v[114:117]
	v_mfma_f32_16x16x32_bf16 v[106:109], v[178:181], v[186:189], v[106:109]
	v_mfma_f32_16x16x32_bf16 v[98:101], v[162:165], v[194:197], v[98:101]
	v_mfma_f32_16x16x32_bf16 v[90:93], v[178:181], v[194:197], v[90:93]
	v_mfma_f32_16x16x32_bf16 v[82:85], v[162:165], v[202:205], v[82:85]
	v_mfma_f32_16x16x32_bf16 v[74:77], v[178:181], v[202:205], v[74:77]
	v_mfma_f32_16x16x32_bf16 v[70:73], v[162:165], v[224:227], v[70:73]
	v_mfma_f32_16x16x32_bf16 v[66:69], v[178:181], v[224:227], v[66:69]
	v_mfma_f32_16x16x32_bf16 v[114:117], v[166:169], v[190:193], v[114:117]
	v_mfma_f32_16x16x32_bf16 v[106:109], v[182:185], v[190:193], v[106:109]
	v_mfma_f32_16x16x32_bf16 v[98:101], v[166:169], v[198:201], v[98:101]
	v_mfma_f32_16x16x32_bf16 v[90:93], v[182:185], v[198:201], v[90:93]
	v_mfma_f32_16x16x32_bf16 v[82:85], v[166:169], v[206:209], v[82:85]
	v_mfma_f32_16x16x32_bf16 v[74:77], v[182:185], v[206:209], v[74:77]
	v_mfma_f32_16x16x32_bf16 v[70:73], v[166:169], v[228:231], v[70:73]
	v_mfma_f32_16x16x32_bf16 v[66:69], v[182:185], v[228:231], v[66:69]
	s_setprio 0
	s_barrier
	s_add_i32 s28, s56, s36
	v_lshl_add_u64 v[140:141], v[140:141], 0, s[88:89]
	s_mov_b32 m0, s28
	ds_read_b128 v[186:189], v145 offset:49152
	ds_read_b128 v[190:193], v145 offset:50176
	ds_read_b128 v[194:197], v145 offset:51200
	ds_read_b128 v[198:201], v145 offset:52224
	ds_read_b128 v[202:205], v145 offset:53248
	ds_read_b128 v[206:209], v145 offset:54272
	ds_read_b128 v[224:227], v145 offset:55296
	ds_read_b128 v[228:231], v145 offset:56320
	global_load_lds_dwordx4 v[140:141], off
	s_add_i32 m0, s28, 0x2000
	s_add_u32 s24, s24, 0x40080
	v_lshl_add_u64 v[140:141], v[210:211], 0, s[88:89]
	s_addc_u32 s25, s25, 0
	s_add_i32 s28, s57, s36
	global_load_lds_dwordx4 v[140:141], off
	v_lshl_add_u64 v[140:141], s[24:25], 0, v[0:1]
	s_mov_b32 m0, s28
	s_nop 0
	global_load_lds_dwordx4 v[140:141], off
	v_lshl_add_u64 v[140:141], s[24:25], 0, v[130:131]
	s_add_i32 m0, s28, 0x2000
	s_nop 0
	global_load_lds_dwordx4 v[140:141], off
	v_lshl_add_u64 v[140:141], v[232:233], 0, s[88:89]
	s_mov_b32 m0, s43
	s_nop 0
	global_load_lds_dwordx4 v[140:141], off
	v_lshl_add_u64 v[140:141], v[234:235], 0, s[88:89]
	s_mov_b32 m0, s47
	s_nop 0
	global_load_lds_dwordx4 v[140:141], off
	s_waitcnt vmcnt(8)
	s_waitcnt lgkmcnt(0)
	s_barrier
	s_setprio 1
	s_waitcnt lgkmcnt(0)
	v_mfma_f32_16x16x32_bf16 v[62:65], v[146:149], v[186:189], v[62:65]
	v_mfma_f32_16x16x32_bf16 v[58:61], v[154:157], v[186:189], v[58:61]
	v_mfma_f32_16x16x32_bf16 v[50:53], v[146:149], v[194:197], v[50:53]
	v_mfma_f32_16x16x32_bf16 v[42:45], v[154:157], v[194:197], v[42:45]
	v_mfma_f32_16x16x32_bf16 v[34:37], v[146:149], v[202:205], v[34:37]
	v_mfma_f32_16x16x32_bf16 v[26:29], v[154:157], v[202:205], v[26:29]
	v_mfma_f32_16x16x32_bf16 v[18:21], v[146:149], v[224:227], v[18:21]
	v_mfma_f32_16x16x32_bf16 v[10:13], v[154:157], v[224:227], v[10:13]
	v_mfma_f32_16x16x32_bf16 v[62:65], v[150:153], v[190:193], v[62:65]
	v_mfma_f32_16x16x32_bf16 v[58:61], v[158:161], v[190:193], v[58:61]
	v_mfma_f32_16x16x32_bf16 v[50:53], v[150:153], v[198:201], v[50:53]
	v_mfma_f32_16x16x32_bf16 v[42:45], v[158:161], v[198:201], v[42:45]
	v_mfma_f32_16x16x32_bf16 v[34:37], v[150:153], v[206:209], v[34:37]
	v_mfma_f32_16x16x32_bf16 v[26:29], v[158:161], v[206:209], v[26:29]
	v_mfma_f32_16x16x32_bf16 v[18:21], v[150:153], v[228:231], v[18:21]
	v_mfma_f32_16x16x32_bf16 v[10:13], v[158:161], v[228:231], v[10:13]
	s_setprio 0
	s_setprio 1
	v_mfma_f32_16x16x32_bf16 v[54:57], v[162:165], v[186:189], v[54:57]
	v_mfma_f32_16x16x32_bf16 v[46:49], v[178:181], v[186:189], v[46:49]
	v_mfma_f32_16x16x32_bf16 v[38:41], v[162:165], v[194:197], v[38:41]
	v_mfma_f32_16x16x32_bf16 v[30:33], v[178:181], v[194:197], v[30:33]
	v_mfma_f32_16x16x32_bf16 v[22:25], v[162:165], v[202:205], v[22:25]
	v_mfma_f32_16x16x32_bf16 v[14:17], v[178:181], v[202:205], v[14:17]
	v_mfma_f32_16x16x32_bf16 v[6:9], v[162:165], v[224:227], v[6:9]
	v_mfma_f32_16x16x32_bf16 v[2:5], v[178:181], v[224:227], v[2:5]
	v_mfma_f32_16x16x32_bf16 v[54:57], v[166:169], v[190:193], v[54:57]
	v_mfma_f32_16x16x32_bf16 v[46:49], v[182:185], v[190:193], v[46:49]
	v_mfma_f32_16x16x32_bf16 v[38:41], v[166:169], v[198:201], v[38:41]
	v_mfma_f32_16x16x32_bf16 v[30:33], v[182:185], v[198:201], v[30:33]
	v_mfma_f32_16x16x32_bf16 v[22:25], v[166:169], v[206:209], v[22:25]
	v_mfma_f32_16x16x32_bf16 v[14:17], v[182:185], v[206:209], v[14:17]
	v_mfma_f32_16x16x32_bf16 v[6:9], v[166:169], v[228:231], v[6:9]
	v_mfma_f32_16x16x32_bf16 v[2:5], v[182:185], v[228:231], v[2:5]
	s_setprio 0
	s_barrier
	s_add_i32 s54, s54, 2
	s_add_u32 s73, s73, 0x100
	s_addc_u32 s52, s52, 0
	s_add_u32 s22, s22, 0x100
	s_addc_u32 s23, s23, 0
	s_cmp_gt_u32 s54, 13
	s_cbranch_scc0 .LBB0_677
	s_and_b64 vcc, exec, s[10:11]
	s_cbranch_vccz .LBB0_680
	s_barrier
